# v034
# speedup vs baseline: 1.0169x; 1.0015x over previous
.LBB0_150:
	s_add_u32 s66, s48, 0xa600000
	s_addc_u32 s67, s49, 0
	s_nop 0
	s_add_u32 s0, s48, 0x100000
	s_addc_u32 s1, s49, 0
	v_writelane_b32 v253, s0, 27
	s_cmpk_gt_i32 s8, 0x5fff
	s_waitcnt vmcnt(27)
	v_mbcnt_lo_u32_b32 v6, -1, 0
	v_writelane_b32 v253, s1, 28
	s_cbranch_scc1 .LBB0_158
	v_mbcnt_hi_u32_b32 v2, -1, v6
	v_and_b32_e32 v1, 64, v2
	v_add_u32_e32 v3, 64, v1
	v_xor_b32_e32 v1, 1, v2
	v_cmp_lt_i32_e32 vcc, v1, v3
	v_xor_b32_e32 v4, 2, v2
	v_readlane_b32 s2, v253, 25
	v_cndmask_b32_e32 v1, v2, v1, vcc
	v_cmp_lt_i32_e32 vcc, v4, v3
	v_readlane_b32 s36, v253, 0
	s_ashr_i32 s9, s8, 31
	v_cndmask_b32_e32 v4, v2, v4, vcc
	s_waitcnt vmcnt(24)
	v_lshlrev_b32_e32 v7, 2, v4
	v_xor_b32_e32 v4, 4, v2
	v_cmp_lt_i32_e32 vcc, v4, v3
	v_readlane_b32 s3, v253, 26
	v_readlane_b32 s37, v253, 1
	v_cndmask_b32_e32 v4, v2, v4, vcc
	v_lshlrev_b32_e32 v8, 2, v4
	v_xor_b32_e32 v4, 8, v2
	v_cmp_lt_i32_e32 vcc, v4, v3
	v_readlane_b32 s0, v253, 27
	s_mov_b32 s4, s2
	v_cndmask_b32_e32 v4, v2, v4, vcc
	s_waitcnt vmcnt(22)
	v_lshlrev_b32_e32 v9, 2, v4
	v_xor_b32_e32 v4, 16, v2
	v_cmp_lt_i32_e32 vcc, v4, v3
	s_ashr_i32 s5, s2, 31
	s_lshl_b64 s[2:3], s[8:9], 13
	v_cndmask_b32_e32 v4, v2, v4, vcc
	v_lshlrev_b32_e32 v10, 2, v4
	v_xor_b32_e32 v4, 32, v2
	v_cmp_lt_i32_e32 vcc, v4, v3
	v_readlane_b32 s38, v253, 2
	v_readlane_b32 s39, v253, 3
	s_mov_b64 s[12:13], s[36:37]
	v_cndmask_b32_e32 v2, v2, v4, vcc
	v_ashrrev_i32_e32 v35, 31, v34
	v_readlane_b32 s1, v253, 28
	v_readlane_b32 s40, v253, 4
	v_readlane_b32 s41, v253, 5
	v_readlane_b32 s42, v253, 6
	v_readlane_b32 s43, v253, 7
	v_readlane_b32 s44, v253, 8
	v_readlane_b32 s45, v253, 9
	v_readlane_b32 s46, v253, 10
	v_readlane_b32 s47, v253, 11
	v_readlane_b32 s48, v253, 12
	v_readlane_b32 s49, v253, 13
	v_readlane_b32 s50, v253, 14
	v_readlane_b32 s51, v253, 15
	s_mov_b64 s[14:15], s[38:39]
	s_add_u32 s12, s12, s2
	v_writelane_b32 v253, s4, 25
	s_mov_b32 s11, 0
	v_lshlrev_b32_e32 v1, 2, v1
	s_waitcnt vmcnt(20)
	v_lshlrev_b32_e32 v11, 2, v2
	v_cmp_gt_i32_e32 vcc, 8, v34
	v_lshl_add_u64 v[2:3], v[34:35], 2, s[0:1]
	v_cmp_eq_u32_e64 s[0:1], 0, v34
	v_lshl_add_u64 v[4:5], v[34:35], 3, s[66:67]
	s_addc_u32 s13, s13, s3
	v_writelane_b32 v253, s5, 26
	s_lshl_b64 s[14:15], s[4:5], 13
	s_movk_i32 s2, 0x1000
	s_branch .LBB0_153

.LBB0_155:
	s_waitcnt vmcnt(2)
	v_lshl_add_u64 v[28:29], v[34:35], 4, s[4:5]
	s_waitcnt lgkmcnt(0)
	s_lshl_b64 s[4:5], s[16:17], 12
	v_lshl_add_u64 v[32:33], v[4:5], 0, s[4:5]
	v_add_co_u32_e64 v44, s[4:5], s2, v28
	global_load_dwordx4 v[12:15], v[28:29], off
	global_load_dwordx4 v[16:19], v[28:29], off offset:1024
	v_addc_co_u32_e64 v45, s[4:5], 0, v29, s[4:5]
	global_load_dwordx4 v[20:23], v[28:29], off offset:2048
	global_load_dwordx4 v[24:27], v[28:29], off offset:3072
	global_load_dwordx4 v[48:51], v[44:45], off
	global_load_dwordx4 v[36:39], v[44:45], off offset:1024
	global_load_dwordx4 v[40:43], v[44:45], off offset:2048
	global_load_dwordx4 v[52:55], v[44:45], off offset:3072
	s_waitcnt vmcnt(7)
	v_cvt_pk_bf16_f32 v56, v12, v13
	v_cvt_pk_bf16_f32 v57, v14, v15
	global_store_dwordx2 v[32:33], v[56:57], off
	v_mul_f32_e32 v13, v13, v13
	v_mul_f32_e32 v15, v15, v15
	v_fmac_f32_e32 v13, v12, v12
	v_fmac_f32_e32 v15, v14, v14
	v_add_f32_e32 v12, v13, v15
	s_waitcnt vmcnt(7)
	v_cvt_pk_bf16_f32 v58, v16, v17
	v_cvt_pk_bf16_f32 v59, v18, v19
	global_store_dwordx2 v[32:33], v[58:59], off offset:512
	v_mul_f32_e32 v13, v17, v17
	v_mul_f32_e32 v14, v19, v19
	v_fmac_f32_e32 v13, v16, v16
	v_fmac_f32_e32 v14, v18, v18
	v_add_f32_e32 v13, v13, v14
	v_add_f32_e32 v12, v12, v13
	s_waitcnt vmcnt(7)
	v_cvt_pk_bf16_f32 v60, v20, v21
	v_cvt_pk_bf16_f32 v61, v22, v23
	global_store_dwordx2 v[32:33], v[60:61], off offset:1024
	v_mul_f32_e32 v13, v21, v21
	v_mul_f32_e32 v14, v23, v23
	v_fmac_f32_e32 v13, v20, v20
	v_fmac_f32_e32 v14, v22, v22
	v_add_f32_e32 v13, v13, v14
	v_add_f32_e32 v12, v12, v13
	s_waitcnt vmcnt(7)
	v_cvt_pk_bf16_f32 v62, v24, v25
	v_cvt_pk_bf16_f32 v63, v26, v27
	global_store_dwordx2 v[32:33], v[62:63], off offset:1536
	v_mul_f32_e32 v13, v25, v25
	v_mul_f32_e32 v14, v27, v27
	v_fmac_f32_e32 v13, v24, v24
	v_fmac_f32_e32 v14, v26, v26
	v_add_f32_e32 v13, v13, v14
	v_add_f32_e32 v12, v12, v13
	s_waitcnt vmcnt(7)
	v_cvt_pk_bf16_f32 v64, v48, v49
	v_cvt_pk_bf16_f32 v65, v50, v51
	global_store_dwordx2 v[32:33], v[64:65], off offset:2048
	v_mul_f32_e32 v13, v49, v49
	v_mul_f32_e32 v14, v51, v51
	v_fmac_f32_e32 v13, v48, v48
	v_fmac_f32_e32 v14, v50, v50
	v_add_f32_e32 v13, v13, v14
	v_add_f32_e32 v12, v12, v13
	s_waitcnt vmcnt(7)
	v_cvt_pk_bf16_f32 v66, v36, v37
	v_cvt_pk_bf16_f32 v67, v38, v39
	global_store_dwordx2 v[32:33], v[66:67], off offset:2560
	v_mul_f32_e32 v13, v37, v37
	v_mul_f32_e32 v14, v39, v39
	v_fmac_f32_e32 v13, v36, v36
	v_fmac_f32_e32 v14, v38, v38
	v_add_f32_e32 v13, v13, v14
	v_add_f32_e32 v12, v12, v13
	s_waitcnt vmcnt(7)
	v_cvt_pk_bf16_f32 v68, v40, v41
	v_cvt_pk_bf16_f32 v69, v42, v43
	global_store_dwordx2 v[32:33], v[68:69], off offset:3072
	v_mul_f32_e32 v13, v41, v41
	v_mul_f32_e32 v14, v43, v43
	v_fmac_f32_e32 v13, v40, v40
	v_fmac_f32_e32 v14, v42, v42
	v_add_f32_e32 v13, v13, v14
	v_add_f32_e32 v12, v12, v13
	s_waitcnt vmcnt(7)
	v_cvt_pk_bf16_f32 v70, v52, v53
	v_cvt_pk_bf16_f32 v71, v54, v55
	global_store_dwordx2 v[32:33], v[70:71], off offset:3584
	v_mul_f32_e32 v13, v53, v53
	v_mul_f32_e32 v14, v55, v55
	v_fmac_f32_e32 v13, v52, v52
	v_fmac_f32_e32 v14, v54, v54
	v_add_f32_e32 v13, v13, v14
	v_add_f32_e32 v12, v12, v13
	ds_bpermute_b32 v13, v1, v12
	s_waitcnt lgkmcnt(0)
	v_add_f32_e32 v12, v12, v13
	ds_bpermute_b32 v13, v7, v12
	s_waitcnt lgkmcnt(0)
	v_add_f32_e32 v12, v12, v13
	ds_bpermute_b32 v13, v8, v12
	s_waitcnt lgkmcnt(0)
	v_add_f32_e32 v12, v12, v13
	ds_bpermute_b32 v13, v9, v12
	s_waitcnt lgkmcnt(0)
	v_add_f32_e32 v12, v12, v13
	ds_bpermute_b32 v13, v10, v12
	s_waitcnt lgkmcnt(0)
	v_add_f32_e32 v12, v12, v13
	ds_bpermute_b32 v13, v11, v12
	s_and_saveexec_b64 s[4:5], vcc
	s_cbranch_execz .LBB0_152
	s_waitcnt lgkmcnt(0)
	v_add_f32_e32 v12, v12, v13
	s_lshl_b64 s[16:17], s[16:17], 5
	v_cndmask_b32_e64 v14, 0, v12, s[0:1]
	v_lshl_add_u64 v[12:13], v[2:3], 0, s[16:17]
	global_store_dword v[12:13], v14, off
	s_branch .LBB0_152

.LBB0_347:
	s_cmpk_gt_i32 s17, 0x47f
	s_mov_b64 s[8:9], -1
	s_cbranch_scc0 .LBB0_349
	s_add_i32 s2, s17, 0xfffffb80
	s_and_b32 s18, s17, 3
	s_lshr_b32 s19, s2, 2
	s_or_b32 s80, s18, s16
	v_readlane_b32 s0, v253, 0
	s_lshl_b64 s[20:21], s[80:81], 2
	v_readlane_b32 s10, v253, 10
	v_readlane_b32 s12, v253, 12
	v_readlane_b32 s11, v253, 11
	v_readlane_b32 s13, v253, 13
	s_add_u32 s10, s12, s20
	s_addc_u32 s11, s13, s21
	v_readlane_b32 s8, v253, 8
	v_readlane_b32 s14, v253, 14
	global_load_dword v0, v1, s[10:11]
	v_readlane_b32 s9, v253, 9
	v_readlane_b32 s15, v253, 15
	s_add_u32 s8, s14, s20
	s_addc_u32 s9, s15, s21
	v_readlane_b32 s7, v253, 7
	s_mul_i32 s7, s18, 0x600000
	s_add_u32 s7, s48, s7
	s_waitcnt vmcnt(3)
	v_mov_b32_e32 v12, v194
	s_waitcnt vmcnt(2)
	v_mov_b32_e32 v6, v195
	v_readlane_b32 s5, v253, 5
	v_readfirstlane_b32 s5, v195
	v_readlane_b32 s0, v255, 27
	v_readlane_b32 s2, v253, 2
	v_readlane_b32 s3, v253, 3
	v_readlane_b32 s4, v253, 4
	v_readlane_b32 s1, v253, 1
	v_readlane_b32 s6, v253, 6
	v_readlane_b32 s4, v255, 51
	s_waitcnt vmcnt(0)
	v_mul_f32_e32 v0, 0x3fb8aa3b, v0
	v_exp_f32_e32 v0, v0
	s_nop 0
	v_mul_f32_e32 v14, 0xbfb8aa3b, v0
	global_load_dword v0, v1, s[8:9]
	s_addc_u32 s9, s49, 0
	s_lshl_b32 s8, s19, 15
	s_add_u32 s8, s7, s8
	v_and_b32_e32 v11, 15, v6
	s_addc_u32 s9, s9, 0
	v_ashrrev_i32_e32 v6, 4, v6
	v_ashrrev_i32_e32 v7, 31, v6
	s_add_i32 s7, 0, 0x10000
	v_and_b32_e32 v70, 31, v12
	s_lshl_b32 s2, s19, 3
	s_lshl_b32 s3, s18, 1
	s_or_b32 s2, s2, s3
	s_waitcnt vmcnt(0)
	v_mul_f32_e32 v0, 0x3fb8aa3b, v0
	v_exp_f32_e32 v0, v0
	s_nop 0
	v_mul_f32_e32 v13, 0xbfb8aa3b, v0
	v_lshlrev_b32_e32 v0, 4, v11
	v_lshl_add_u64 v[4:5], s[8:9], 0, v[0:1]
	s_mov_b64 s[8:9], 0x29e00000
	v_lshl_add_u64 v[2:3], v[4:5], 0, s[8:9]
	s_mov_b64 s[8:9], 0x2b600000
	v_lshl_add_u64 v[8:9], v[4:5], 0, s[8:9]
	v_lshlrev_b32_e32 v5, 2, v6
	v_bfe_u32 v0, v6, 2, 2
	v_and_b32_e32 v5, 12, v5
	v_lshlrev_b32_e32 v4, 8, v6
	v_bitop3_b32 v5, v5, v11, v0 bitop3:0x36
	v_lshl_or_b32 v15, v5, 4, v4
	v_lshlrev_b64 v[4:5], 8, v[6:7]
	s_mov_b64 s[8:9], 0x2000
	v_lshl_add_u64 v[120:121], v[2:3], 0, v[4:5]
	v_lshl_add_u64 v[122:123], v[8:9], 0, v[4:5]
	global_load_dwordx4 v[88:91], v[120:121], off
	global_load_dwordx4 v[92:95], v[122:123], off
	v_lshl_add_u64 v[120:121], v[120:121], 0, s[8:9]
	v_lshl_add_u64 v[122:123], v[122:123], 0, s[8:9]
	global_load_dwordx4 v[96:99], v[120:121], off
	global_load_dwordx4 v[100:103], v[122:123], off
	v_lshl_add_u64 v[120:121], v[120:121], 0, s[8:9]
	v_lshl_add_u64 v[122:123], v[122:123], 0, s[8:9]
	global_load_dwordx4 v[104:107], v[120:121], off
	global_load_dwordx4 v[108:111], v[122:123], off
	v_lshl_add_u64 v[120:121], v[120:121], 0, s[8:9]
	v_lshl_add_u64 v[122:123], v[122:123], 0, s[8:9]
	global_load_dwordx4 v[112:115], v[120:121], off
	global_load_dwordx4 v[116:119], v[122:123], off
	v_sub_u32_e32 v4, 0x7f, v6
	v_cvt_f32_i32_e32 v4, v4
	v_cvt_f32_i32_e32 v5, v6
	v_add_u32_e32 v7, 0, v15
	s_lshr_b32 s8, s5, 8
	v_mul_f32_e32 v4, v14, v4
	v_exp_f32_e32 v4, v4
	v_mul_f32_e32 v5, v13, v5
	v_exp_f32_e32 v5, v5
	s_bfe_u32 s5, s5, 0x20006
	v_mul_f32_e32 v4, 0x3db504f3, v4
	s_lshl_b32 s9, s8, 15
	v_mul_f32_e32 v10, 0x3db504f3, v5
	s_add_i32 s9, s9, 0
	s_add_i32 s80, s2, s8
	s_lshl_b64 s[2:3], s[80:81], 16
	s_waitcnt vmcnt(7)
	v_mov_b32_e32 v16, v88
	v_mov_b32_e32 v17, v89
	v_mov_b32_e32 v18, v90
	v_mov_b32_e32 v19, v91
	v_lshlrev_b32_e32 v24, 16, v16
	v_and_b32_e32 v25, 0xffff0000, v16
	v_pk_mul_f32 v[26:27], v[4:5], v[24:25] op_sel_hi:[0,1]
	v_cvt_pk_bf16_f32 v16, v26, v27
	v_lshlrev_b32_e32 v26, 16, v17
	v_and_b32_e32 v27, 0xffff0000, v17
	v_pk_mul_f32 v[28:29], v[4:5], v[26:27] op_sel_hi:[0,1]
	v_cvt_pk_bf16_f32 v17, v28, v29
	v_lshlrev_b32_e32 v28, 16, v18
	v_and_b32_e32 v29, 0xffff0000, v18
	v_pk_mul_f32 v[30:31], v[4:5], v[28:29] op_sel_hi:[0,1]
	v_cvt_pk_bf16_f32 v18, v30, v31
	v_lshlrev_b32_e32 v30, 16, v19
	v_and_b32_e32 v31, 0xffff0000, v19
	v_pk_mul_f32 v[4:5], v[4:5], v[30:31] op_sel_hi:[0,1]
	v_cvt_pk_bf16_f32 v19, v4, v5
	v_pk_mul_f32 v[4:5], v[10:11], v[24:25] op_sel_hi:[0,1]
	ds_write_b128 v7, v[16:19]
	v_cvt_pk_bf16_f32 v16, v4, v5
	v_pk_mul_f32 v[4:5], v[10:11], v[26:27] op_sel_hi:[0,1]
	v_cvt_pk_bf16_f32 v17, v4, v5
	v_pk_mul_f32 v[4:5], v[10:11], v[28:29] op_sel_hi:[0,1]
	v_cvt_pk_bf16_f32 v18, v4, v5
	v_pk_mul_f32 v[4:5], v[10:11], v[30:31] op_sel_hi:[0,1]
	v_cvt_pk_bf16_f32 v19, v4, v5
	v_add_u32_e32 v4, s7, v15
	s_waitcnt vmcnt(6)
	v_mov_b32_e32 v20, v92
	v_mov_b32_e32 v21, v93
	v_mov_b32_e32 v22, v94
	v_mov_b32_e32 v23, v95
	ds_write_b128 v4, v[20:23]
	v_add_u32_e32 v4, 32, v6
	ds_write_b128 v7, v[16:19] offset:32768
	v_lshlrev_b32_e32 v7, 2, v4
	v_and_b32_e32 v7, 12, v7
	v_lshlrev_b32_e32 v5, 8, v4
	v_bitop3_b32 v7, v7, v11, v0 bitop3:0x36
	v_lshl_or_b32 v7, v7, 4, v5
	v_ashrrev_i32_e32 v5, 31, v4
	v_lshlrev_b64 v[20:21], 8, v[4:5]
	v_lshl_add_u64 v[16:17], v[2:3], 0, v[20:21]
	v_lshl_add_u64 v[20:21], v[8:9], 0, v[20:21]
	v_sub_u32_e32 v5, 0x5f, v6
	v_cvt_f32_i32_e32 v5, v5
	v_cvt_f32_i32_e32 v4, v4
	v_mul_f32_e32 v5, v14, v5
	v_exp_f32_e32 v5, v5
	v_mul_f32_e32 v4, v13, v4
	v_exp_f32_e32 v4, v4
	v_mul_f32_e32 v10, 0x3db504f3, v5
	v_mul_f32_e32 v4, 0x3db504f3, v4
	s_waitcnt vmcnt(5)
	v_mov_b32_e32 v16, v96
	v_mov_b32_e32 v17, v97
	v_mov_b32_e32 v18, v98
	v_mov_b32_e32 v19, v99
	v_lshlrev_b32_e32 v24, 16, v16
	v_and_b32_e32 v25, 0xffff0000, v16
	v_pk_mul_f32 v[26:27], v[10:11], v[24:25] op_sel_hi:[0,1]
	v_cvt_pk_bf16_f32 v16, v26, v27
	v_lshlrev_b32_e32 v26, 16, v17
	v_and_b32_e32 v27, 0xffff0000, v17
	v_pk_mul_f32 v[28:29], v[10:11], v[26:27] op_sel_hi:[0,1]
	v_cvt_pk_bf16_f32 v17, v28, v29
	v_lshlrev_b32_e32 v28, 16, v18
	v_and_b32_e32 v29, 0xffff0000, v18
	v_pk_mul_f32 v[30:31], v[10:11], v[28:29] op_sel_hi:[0,1]
	v_cvt_pk_bf16_f32 v18, v30, v31
	v_lshlrev_b32_e32 v30, 16, v19
	v_and_b32_e32 v31, 0xffff0000, v19
	v_pk_mul_f32 v[32:33], v[10:11], v[30:31] op_sel_hi:[0,1]
	v_cvt_pk_bf16_f32 v19, v32, v33
	v_add_u32_e32 v10, 0, v7
	ds_write_b128 v10, v[16:19]
	v_pk_mul_f32 v[16:17], v[4:5], v[24:25] op_sel_hi:[0,1]
	v_pk_mul_f32 v[18:19], v[4:5], v[26:27] op_sel_hi:[0,1]
	v_cvt_pk_bf16_f32 v16, v16, v17
	v_cvt_pk_bf16_f32 v17, v18, v19
	v_pk_mul_f32 v[18:19], v[4:5], v[28:29] op_sel_hi:[0,1]
	v_pk_mul_f32 v[4:5], v[4:5], v[30:31] op_sel_hi:[0,1]
	v_cvt_pk_bf16_f32 v18, v18, v19
	v_cvt_pk_bf16_f32 v19, v4, v5
	v_add_u32_e32 v4, s7, v7
	s_waitcnt vmcnt(4)
	v_mov_b32_e32 v20, v100
	v_mov_b32_e32 v21, v101
	v_mov_b32_e32 v22, v102
	v_mov_b32_e32 v23, v103
	ds_write_b128 v4, v[20:23]
	v_add_u32_e32 v4, 64, v6
	v_lshlrev_b32_e32 v7, 2, v4
	v_and_b32_e32 v7, 12, v7
	v_lshlrev_b32_e32 v5, 8, v4
	v_bitop3_b32 v7, v7, v11, v0 bitop3:0x36
	v_lshl_or_b32 v7, v7, 4, v5
	v_ashrrev_i32_e32 v5, 31, v4
	v_lshlrev_b64 v[20:21], 8, v[4:5]
	ds_write_b128 v10, v[16:19] offset:32768
	v_lshl_add_u64 v[16:17], v[2:3], 0, v[20:21]
	v_lshl_add_u64 v[20:21], v[8:9], 0, v[20:21]
	v_sub_u32_e32 v5, 63, v6
	v_cvt_f32_i32_e32 v5, v5
	v_cvt_f32_i32_e32 v4, v4
	v_mul_f32_e32 v5, v14, v5
	v_exp_f32_e32 v5, v5
	v_mul_f32_e32 v4, v13, v4
	v_exp_f32_e32 v4, v4
	v_mul_f32_e32 v10, 0x3db504f3, v5
	v_mul_f32_e32 v4, 0x3db504f3, v4
	s_waitcnt vmcnt(3)
	v_mov_b32_e32 v16, v104
	v_mov_b32_e32 v17, v105
	v_mov_b32_e32 v18, v106
	v_mov_b32_e32 v19, v107
	v_lshlrev_b32_e32 v24, 16, v16
	v_and_b32_e32 v25, 0xffff0000, v16
	v_pk_mul_f32 v[26:27], v[10:11], v[24:25] op_sel_hi:[0,1]
	v_cvt_pk_bf16_f32 v16, v26, v27
	v_lshlrev_b32_e32 v26, 16, v17
	v_and_b32_e32 v27, 0xffff0000, v17
	v_pk_mul_f32 v[28:29], v[10:11], v[26:27] op_sel_hi:[0,1]
	v_cvt_pk_bf16_f32 v17, v28, v29
	v_lshlrev_b32_e32 v28, 16, v18
	v_and_b32_e32 v29, 0xffff0000, v18
	v_pk_mul_f32 v[30:31], v[10:11], v[28:29] op_sel_hi:[0,1]
	v_cvt_pk_bf16_f32 v18, v30, v31
	v_lshlrev_b32_e32 v30, 16, v19
	v_and_b32_e32 v31, 0xffff0000, v19
	v_pk_mul_f32 v[32:33], v[10:11], v[30:31] op_sel_hi:[0,1]
	v_cvt_pk_bf16_f32 v19, v32, v33
	v_add_u32_e32 v10, 0, v7
	ds_write_b128 v10, v[16:19]
	v_pk_mul_f32 v[16:17], v[4:5], v[24:25] op_sel_hi:[0,1]
	v_pk_mul_f32 v[18:19], v[4:5], v[26:27] op_sel_hi:[0,1]
	v_cvt_pk_bf16_f32 v16, v16, v17
	v_cvt_pk_bf16_f32 v17, v18, v19
	v_pk_mul_f32 v[18:19], v[4:5], v[28:29] op_sel_hi:[0,1]
	v_pk_mul_f32 v[4:5], v[4:5], v[30:31] op_sel_hi:[0,1]
	v_cvt_pk_bf16_f32 v18, v18, v19
	v_cvt_pk_bf16_f32 v19, v4, v5
	ds_write_b128 v10, v[16:19] offset:32768
	v_add_u32_e32 v10, 0x60, v6
	v_lshlrev_b32_e32 v5, 2, v10
	v_and_b32_e32 v5, 12, v5
	v_bitop3_b32 v0, v5, v11, v0 bitop3:0x36
	v_ashrrev_i32_e32 v11, 31, v10
	v_add_u32_e32 v4, s7, v7
	v_lshlrev_b64 v[16:17], 8, v[10:11]
	s_waitcnt vmcnt(2)
	v_mov_b32_e32 v20, v108
	v_mov_b32_e32 v21, v109
	v_mov_b32_e32 v22, v110
	v_mov_b32_e32 v23, v111
	ds_write_b128 v4, v[20:23]
	v_lshlrev_b32_e32 v4, 8, v10
	v_lshl_add_u64 v[2:3], v[2:3], 0, v[16:17]
	v_lshl_or_b32 v24, v0, 4, v4
	v_lshl_add_u64 v[8:9], v[8:9], 0, v[16:17]
	v_sub_u32_e32 v0, 31, v6
	v_cvt_f32_i32_e32 v0, v0
	v_cvt_f32_i32_e32 v6, v10
	v_mul_f32_e32 v0, v14, v0
	v_exp_f32_e32 v0, v0
	v_mul_f32_e32 v6, v13, v6
	v_exp_f32_e32 v6, v6
	v_mul_f32_e32 v0, 0x3db504f3, v0
	v_mul_f32_e32 v6, 0x3db504f3, v6
	s_waitcnt vmcnt(1)
	v_mov_b32_e32 v2, v112
	v_mov_b32_e32 v3, v113
	v_mov_b32_e32 v4, v114
	v_mov_b32_e32 v5, v115
	v_lshlrev_b32_e32 v8, 16, v2
	v_and_b32_e32 v9, 0xffff0000, v2
	v_pk_mul_f32 v[10:11], v[0:1], v[8:9] op_sel_hi:[0,1]
	v_cvt_pk_bf16_f32 v2, v10, v11
	v_lshlrev_b32_e32 v10, 16, v3
	v_and_b32_e32 v11, 0xffff0000, v3
	v_pk_mul_f32 v[14:15], v[0:1], v[10:11] op_sel_hi:[0,1]
	v_cvt_pk_bf16_f32 v3, v14, v15
	v_lshlrev_b32_e32 v14, 16, v4
	v_and_b32_e32 v15, 0xffff0000, v4
	v_pk_mul_f32 v[20:21], v[0:1], v[14:15] op_sel_hi:[0,1]
	v_cvt_pk_bf16_f32 v4, v20, v21
	v_lshlrev_b32_e32 v20, 16, v5
	v_and_b32_e32 v21, 0xffff0000, v5
	v_pk_mul_f32 v[22:23], v[0:1], v[20:21] op_sel_hi:[0,1]
	v_cvt_pk_bf16_f32 v5, v22, v23
	v_add_u32_e32 v0, 0, v24
	ds_write_b128 v0, v[2:5]
	v_pk_mul_f32 v[2:3], v[6:7], v[8:9] op_sel_hi:[0,1]
	v_pk_mul_f32 v[4:5], v[6:7], v[10:11] op_sel_hi:[0,1]
	v_cvt_pk_bf16_f32 v2, v2, v3
	v_cvt_pk_bf16_f32 v3, v4, v5
	v_pk_mul_f32 v[4:5], v[6:7], v[14:15] op_sel_hi:[0,1]
	v_pk_mul_f32 v[6:7], v[6:7], v[20:21] op_sel_hi:[0,1]
	v_cvt_pk_bf16_f32 v4, v4, v5
	v_cvt_pk_bf16_f32 v5, v6, v7
	ds_write_b128 v0, v[2:5] offset:32768
	v_add_u32_e32 v0, s7, v24
	s_waitcnt vmcnt(0)
	v_mov_b32_e32 v16, v116
	v_mov_b32_e32 v17, v117
	v_mov_b32_e32 v18, v118
	v_mov_b32_e32 v19, v119
	ds_write_b128 v0, v[16:19]
	v_ashrrev_i32_e32 v0, 5, v12
	v_bfe_u32 v2, v12, 2, 2
	v_lshrrev_b32_e32 v4, 3, v12
	v_bfe_u32 v5, v12, 1, 1
	v_lshlrev_b32_e32 v9, 1, v0
	v_lshlrev_b32_e32 v3, 3, v0
	v_and_or_b32 v4, v4, 2, v5
	v_lshlrev_b32_e32 v5, 2, v2
	v_and_b32_e32 v9, 2, v9
	v_lshlrev_b32_e32 v6, 3, v12
	v_or_b32_e32 v7, v3, v2
	v_bitop3_b32 v10, v9, v4, v5 bitop3:0x36
	v_or_b32_e32 v3, 4, v3
	v_and_b32_e32 v6, 8, v6
	v_lshlrev_b32_e32 v8, 8, v7
	v_lshlrev_b32_e32 v10, 4, v10
	v_or_b32_e32 v2, v3, v2
	v_bfe_u32 v3, v3, 2, 2
	v_or3_b32 v77, v10, v8, v6
	v_bitop3_b32 v10, v3, v4, v5 bitop3:0x36
	v_lshlrev_b32_e32 v2, 8, v2
	v_lshlrev_b32_e32 v10, 4, v10
	v_or3_b32 v78, v10, v2, v6
	v_or_b32_e32 v10, 4, v4
	v_bitop3_b32 v11, v9, v10, v5 bitop3:0x36
	v_bitop3_b32 v10, v3, v10, v5 bitop3:0x36
	v_lshlrev_b32_e32 v10, 4, v10
	v_lshlrev_b32_e32 v11, 4, v11
	v_or3_b32 v75, v10, v2, v6
	v_or_b32_e32 v10, 8, v4
	v_or3_b32 v76, v11, v8, v6
	v_bitop3_b32 v11, v9, v10, v5 bitop3:0x36
	v_bitop3_b32 v10, v3, v10, v5 bitop3:0x36
	v_lshlrev_b32_e32 v10, 4, v10
	v_or3_b32 v73, v10, v2, v6
	v_or_b32_e32 v10, 12, v4
	v_bitop3_b32 v3, v3, v10, v5 bitop3:0x36
	v_lshlrev_b32_e32 v3, 4, v3
	v_or3_b32 v71, v3, v2, v6
	v_lshl_or_b32 v2, s5, 2, v4
	v_or_b32_e32 v4, 4, v7
	v_lshlrev_b32_e32 v11, 4, v11
	v_bfe_u32 v7, v4, 2, 2
	v_or3_b32 v74, v11, v8, v6
	v_bitop3_b32 v11, v9, v10, v5 bitop3:0x36
	v_bitop3_b32 v3, v9, v2, v5 bitop3:0x36
	v_bitop3_b32 v2, v7, v2, v5 bitop3:0x36
	v_lshlrev_b32_e32 v11, 4, v11
	v_lshlrev_b32_e32 v4, 8, v4
	v_lshl_add_u32 v3, v3, 4, s9
	v_lshl_add_u32 v2, v2, 4, s9
	v_or3_b32 v72, v11, v8, v6
	v_add3_u32 v80, v3, v8, v6
	v_add3_u32 v79, v2, v4, v6
	v_add_u32_e32 v6, s7, v77
	v_add_u32_e32 v8, s7, v78
	s_waitcnt lgkmcnt(0)
	s_barrier
	ds_read_b64_tr_b16 v[2:3], v80
	ds_read_b64_tr_b16 v[4:5], v79
	ds_read_b64_tr_b16 v[6:7], v6
	ds_read_b64_tr_b16 v[8:9], v8
	s_waitcnt lgkmcnt(0)
	v_mfma_f32_32x32x16_bf16 v[50:65], v[2:5], v[6:9], 0
	v_add_u32_e32 v6, s7, v76
	v_add_u32_e32 v8, s7, v75
	ds_read_b64_tr_b16 v[6:7], v6
	ds_read_b64_tr_b16 v[8:9], v8
	v_add_u32_e32 v81, s0, v77
	v_lshl_or_b32 v0, v0, 9, v70
	s_waitcnt lgkmcnt(0)
	v_mfma_f32_32x32x16_bf16 v[34:49], v[2:5], v[6:9], 0
	v_add_u32_e32 v6, s7, v74
	v_add_u32_e32 v8, s7, v73
	ds_read_b64_tr_b16 v[6:7], v6
	ds_read_b64_tr_b16 v[8:9], v8
	s_waitcnt lgkmcnt(0)
	v_mfma_f32_32x32x16_bf16 v[18:33], v[2:5], v[6:9], 0
	v_add_u32_e32 v6, s7, v72
	v_add_u32_e32 v8, s7, v71
	ds_read_b64_tr_b16 v[6:7], v6
	ds_read_b64_tr_b16 v[8:9], v8
	ds_read_b64_tr_b16 v[66:67], v80 offset:4096
	ds_read_b64_tr_b16 v[68:69], v79 offset:4096
	ds_read_b64_tr_b16 v[82:83], v81
	v_add_u32_e32 v81, s0, v78
	ds_read_b64_tr_b16 v[84:85], v81
	v_add_u32_e32 v81, s0, v76
	s_waitcnt lgkmcnt(0)
	v_mfma_f32_32x32x16_bf16 v[50:65], v[66:69], v[82:85], v[50:65]
	ds_read_b64_tr_b16 v[82:83], v81
	v_add_u32_e32 v81, s0, v75
	ds_read_b64_tr_b16 v[84:85], v81
	v_add_u32_e32 v81, s0, v74
	s_add_i32 s7, 0, 0x12000
	s_waitcnt lgkmcnt(0)
	v_mfma_f32_32x32x16_bf16 v[34:49], v[66:69], v[82:85], v[34:49]
	ds_read_b64_tr_b16 v[82:83], v81
	v_add_u32_e32 v81, s0, v73
	ds_read_b64_tr_b16 v[84:85], v81
	v_add_u32_e32 v81, s0, v72
	v_mfma_f32_32x32x16_bf16 v[2:17], v[2:5], v[6:9], 0
	s_waitcnt lgkmcnt(0)
	v_mfma_f32_32x32x16_bf16 v[18:33], v[66:69], v[82:85], v[18:33]
	ds_read_b64_tr_b16 v[82:83], v81
	v_add_u32_e32 v81, s0, v71
	ds_read_b64_tr_b16 v[84:85], v81
	v_add_u32_e32 v81, s7, v77
	v_readlane_b32 s0, v255, 28
	s_waitcnt lgkmcnt(0)
	v_mfma_f32_32x32x16_bf16 v[2:17], v[66:69], v[82:85], v[2:17]
	ds_read_b64_tr_b16 v[66:67], v80 offset:8192
	ds_read_b64_tr_b16 v[68:69], v79 offset:8192
	ds_read_b64_tr_b16 v[82:83], v81
	v_add_u32_e32 v81, s7, v78
	ds_read_b64_tr_b16 v[84:85], v81
	v_add_u32_e32 v81, s7, v76
	s_waitcnt lgkmcnt(0)
	v_mfma_f32_32x32x16_bf16 v[50:65], v[66:69], v[82:85], v[50:65]
	ds_read_b64_tr_b16 v[82:83], v81
	v_add_u32_e32 v81, s7, v75
	ds_read_b64_tr_b16 v[84:85], v81
	v_add_u32_e32 v81, s7, v74
	s_waitcnt lgkmcnt(0)
	v_mfma_f32_32x32x16_bf16 v[34:49], v[66:69], v[82:85], v[34:49]
	ds_read_b64_tr_b16 v[82:83], v81
	v_add_u32_e32 v81, s7, v73
	ds_read_b64_tr_b16 v[84:85], v81
	v_add_u32_e32 v81, s7, v72
	s_waitcnt lgkmcnt(0)
	v_mfma_f32_32x32x16_bf16 v[18:33], v[66:69], v[82:85], v[18:33]
	ds_read_b64_tr_b16 v[82:83], v81
	v_add_u32_e32 v81, s7, v71
	ds_read_b64_tr_b16 v[84:85], v81
	v_add_u32_e32 v81, s0, v77
	s_add_i32 s7, 0, 0x14000
	s_waitcnt lgkmcnt(0)
	v_mfma_f32_32x32x16_bf16 v[2:17], v[66:69], v[82:85], v[2:17]
	ds_read_b64_tr_b16 v[66:67], v80 offset:12288
	ds_read_b64_tr_b16 v[68:69], v79 offset:12288
	ds_read_b64_tr_b16 v[82:83], v81
	v_add_u32_e32 v81, s0, v78
	ds_read_b64_tr_b16 v[84:85], v81
	v_add_u32_e32 v81, s0, v76
	s_waitcnt lgkmcnt(0)
	v_mfma_f32_32x32x16_bf16 v[50:65], v[66:69], v[82:85], v[50:65]
	ds_read_b64_tr_b16 v[82:83], v81
	v_add_u32_e32 v81, s0, v75
	ds_read_b64_tr_b16 v[84:85], v81
	v_add_u32_e32 v81, s0, v74
	s_waitcnt lgkmcnt(0)
	v_mfma_f32_32x32x16_bf16 v[34:49], v[66:69], v[82:85], v[34:49]
	ds_read_b64_tr_b16 v[82:83], v81
	v_add_u32_e32 v81, s0, v73
	ds_read_b64_tr_b16 v[84:85], v81
	v_add_u32_e32 v81, s0, v72
	s_waitcnt lgkmcnt(0)
	v_mfma_f32_32x32x16_bf16 v[18:33], v[66:69], v[82:85], v[18:33]
	ds_read_b64_tr_b16 v[82:83], v81
	v_add_u32_e32 v81, s0, v71
	ds_read_b64_tr_b16 v[84:85], v81
	v_add_u32_e32 v81, s7, v77
	v_readlane_b32 s0, v255, 29
	s_waitcnt lgkmcnt(0)
	v_mfma_f32_32x32x16_bf16 v[2:17], v[66:69], v[82:85], v[2:17]
	ds_read_b64_tr_b16 v[66:67], v80 offset:16384
	ds_read_b64_tr_b16 v[68:69], v79 offset:16384
	ds_read_b64_tr_b16 v[82:83], v81
	v_add_u32_e32 v81, s7, v78
	ds_read_b64_tr_b16 v[84:85], v81
	v_add_u32_e32 v81, s7, v76
	s_waitcnt lgkmcnt(0)
	v_mfma_f32_32x32x16_bf16 v[50:65], v[66:69], v[82:85], v[50:65]
	ds_read_b64_tr_b16 v[82:83], v81
	v_add_u32_e32 v81, s7, v75
	ds_read_b64_tr_b16 v[84:85], v81
	v_add_u32_e32 v81, s7, v74
	s_waitcnt lgkmcnt(0)
	v_mfma_f32_32x32x16_bf16 v[34:49], v[66:69], v[82:85], v[34:49]
	ds_read_b64_tr_b16 v[82:83], v81
	v_add_u32_e32 v81, s7, v73
	ds_read_b64_tr_b16 v[84:85], v81
	v_add_u32_e32 v81, s7, v72
	s_waitcnt lgkmcnt(0)
	v_mfma_f32_32x32x16_bf16 v[18:33], v[66:69], v[82:85], v[18:33]
	ds_read_b64_tr_b16 v[82:83], v81
	v_add_u32_e32 v81, s7, v71
	ds_read_b64_tr_b16 v[84:85], v81
	v_add_u32_e32 v81, s0, v77
	s_add_i32 s7, 0, 0x16000
	s_add_u32 s8, s30, s2
	s_addc_u32 s9, s31, s3
	s_waitcnt lgkmcnt(0)
	v_mfma_f32_32x32x16_bf16 v[2:17], v[66:69], v[82:85], v[2:17]
	ds_read_b64_tr_b16 v[66:67], v80 offset:20480
	ds_read_b64_tr_b16 v[68:69], v79 offset:20480
	ds_read_b64_tr_b16 v[82:83], v81
	v_add_u32_e32 v81, s0, v78
	ds_read_b64_tr_b16 v[84:85], v81
	v_add_u32_e32 v81, s0, v76
	s_lshl_b32 s2, s5, 12
	s_or_b32 s3, s2, 0x80
	s_waitcnt lgkmcnt(0)
	v_mfma_f32_32x32x16_bf16 v[50:65], v[66:69], v[82:85], v[50:65]
	ds_read_b64_tr_b16 v[82:83], v81
	v_add_u32_e32 v81, s0, v75
	ds_read_b64_tr_b16 v[84:85], v81
	v_add_u32_e32 v81, s0, v74
	s_or_b32 s5, s2, 0x100
	s_or_b32 s10, s2, 0x400
	s_or_b32 s11, s2, 0x480
	s_waitcnt lgkmcnt(0)
	v_mfma_f32_32x32x16_bf16 v[34:49], v[66:69], v[82:85], v[34:49]
	ds_read_b64_tr_b16 v[82:83], v81
	v_add_u32_e32 v81, s0, v73
	ds_read_b64_tr_b16 v[84:85], v81
	v_add_u32_e32 v81, s0, v72
	s_or_b32 s12, s2, 0x500
	s_or_b32 s13, s2, 0x580
	s_or_b32 s14, s2, 0x800
	s_waitcnt lgkmcnt(0)
	v_mfma_f32_32x32x16_bf16 v[18:33], v[66:69], v[82:85], v[18:33]
	ds_read_b64_tr_b16 v[82:83], v81
	v_add_u32_e32 v81, s0, v71
	ds_read_b64_tr_b16 v[84:85], v81
	v_add_u32_e32 v81, s7, v77
	v_readlane_b32 s0, v255, 30
	s_or_b32 s15, s2, 0x880
	s_or_b32 s18, s2, 0x900
	s_waitcnt lgkmcnt(0)
	v_mfma_f32_32x32x16_bf16 v[2:17], v[66:69], v[82:85], v[2:17]
	ds_read_b64_tr_b16 v[66:67], v80 offset:24576
	ds_read_b64_tr_b16 v[68:69], v79 offset:24576
	ds_read_b64_tr_b16 v[82:83], v81
	v_add_u32_e32 v81, s7, v78
	ds_read_b64_tr_b16 v[84:85], v81
	v_add_u32_e32 v81, s7, v76
	v_add_u32_e32 v77, s0, v77
	v_add_u32_e32 v76, s0, v76
	s_waitcnt lgkmcnt(0)
	v_mfma_f32_32x32x16_bf16 v[50:65], v[66:69], v[82:85], v[50:65]
	ds_read_b64_tr_b16 v[82:83], v81
	v_add_u32_e32 v81, s7, v75
	ds_read_b64_tr_b16 v[84:85], v81
	v_add_u32_e32 v81, s7, v74
	v_add_u32_e32 v75, s0, v75
	v_add_u32_e32 v74, s0, v74
	s_or_b32 s19, s2, 0x980
	s_waitcnt lgkmcnt(0)
	v_mfma_f32_32x32x16_bf16 v[34:49], v[66:69], v[82:85], v[34:49]
	ds_read_b64_tr_b16 v[82:83], v81
	v_add_u32_e32 v81, s7, v73
	ds_read_b64_tr_b16 v[84:85], v81
	v_add_u32_e32 v81, s7, v72
	v_add_u32_e32 v73, s0, v73
	v_add_u32_e32 v72, s0, v72
	s_or_b32 s20, s2, 0xc00
	s_waitcnt lgkmcnt(0)
	v_mfma_f32_32x32x16_bf16 v[18:33], v[66:69], v[82:85], v[18:33]
	ds_read_b64_tr_b16 v[82:83], v81
	v_add_u32_e32 v81, s7, v71
	ds_read_b64_tr_b16 v[84:85], v81
	v_add_u32_e32 v71, s0, v71
	s_or_b32 s7, s2, 0x180
	s_or_b32 s21, s2, 0xc80
	s_or_b32 s22, s2, 0xd00
	s_waitcnt lgkmcnt(0)
	v_mfma_f32_32x32x16_bf16 v[2:17], v[66:69], v[82:85], v[2:17]
	ds_read_b64_tr_b16 v[66:67], v80 offset:28672
	ds_read_b64_tr_b16 v[68:69], v79 offset:28672
	ds_read_b64_tr_b16 v[80:81], v77
	v_add_u32_e32 v77, s0, v78
	ds_read_b64_tr_b16 v[82:83], v77
	ds_read_b64_tr_b16 v[78:79], v75
	ds_read_b64_tr_b16 v[76:77], v76
	ds_read_b64_tr_b16 v[74:75], v74
	s_waitcnt lgkmcnt(1)
	v_mfma_f32_32x32x16_bf16 v[34:49], v[66:69], v[76:79], v[34:49]
	ds_read_b64_tr_b16 v[76:77], v73
	ds_read_b64_tr_b16 v[72:73], v72
	s_or_b32 s23, s2, 0xd80
	v_mfma_f32_32x32x16_bf16 v[50:65], v[66:69], v[80:83], v[50:65]
	s_waitcnt lgkmcnt(1)
	v_mfma_f32_32x32x16_bf16 v[18:33], v[66:69], v[74:77], v[18:33]
	ds_read_b64_tr_b16 v[74:75], v71
	s_waitcnt lgkmcnt(0)
	v_mfma_f32_32x32x16_bf16 v[2:17], v[66:69], v[72:75], v[2:17]
	v_add_u32_e32 v66, s2, v0
	v_ashrrev_i32_e32 v67, 31, v66
	v_lshl_add_u64 v[66:67], v[66:67], 2, s[8:9]
	s_nop 3
	global_store_dword v[66:67], v50, off
	v_add_u32_e32 v66, s3, v0
	v_ashrrev_i32_e32 v67, 31, v66
	v_lshl_add_u64 v[66:67], v[66:67], 2, s[8:9]
	v_add_u32_e32 v50, s5, v0
	global_store_dword v[66:67], v51, off
	v_ashrrev_i32_e32 v51, 31, v50
	v_lshl_add_u64 v[50:51], v[50:51], 2, s[8:9]
	global_store_dword v[50:51], v52, off
	v_add_u32_e32 v50, s7, v0
	v_ashrrev_i32_e32 v51, 31, v50
	v_lshl_add_u64 v[50:51], v[50:51], 2, s[8:9]
	global_store_dword v[50:51], v53, off
	v_add_u32_e32 v50, s10, v0
	v_ashrrev_i32_e32 v51, 31, v50
	v_lshl_add_u64 v[50:51], v[50:51], 2, s[8:9]
	global_store_dword v[50:51], v54, off
	v_add_u32_e32 v50, s11, v0
	v_ashrrev_i32_e32 v51, 31, v50
	v_lshl_add_u64 v[50:51], v[50:51], 2, s[8:9]
	global_store_dword v[50:51], v55, off
	v_add_u32_e32 v50, s12, v0
	v_ashrrev_i32_e32 v51, 31, v50
	v_lshl_add_u64 v[50:51], v[50:51], 2, s[8:9]
	global_store_dword v[50:51], v56, off
	v_add_u32_e32 v50, s13, v0
	v_ashrrev_i32_e32 v51, 31, v50
	v_lshl_add_u64 v[50:51], v[50:51], 2, s[8:9]
	global_store_dword v[50:51], v57, off
	v_add_u32_e32 v50, s14, v0
	v_ashrrev_i32_e32 v51, 31, v50
	v_lshl_add_u64 v[50:51], v[50:51], 2, s[8:9]
	global_store_dword v[50:51], v58, off
	v_add_u32_e32 v50, s15, v0
	v_ashrrev_i32_e32 v51, 31, v50
	v_lshl_add_u64 v[50:51], v[50:51], 2, s[8:9]
	global_store_dword v[50:51], v59, off
	v_add_u32_e32 v50, s18, v0
	v_ashrrev_i32_e32 v51, 31, v50
	v_lshl_add_u64 v[50:51], v[50:51], 2, s[8:9]
	global_store_dword v[50:51], v60, off
	v_add_u32_e32 v50, s19, v0
	v_ashrrev_i32_e32 v51, 31, v50
	v_lshl_add_u64 v[50:51], v[50:51], 2, s[8:9]
	global_store_dword v[50:51], v61, off
	v_add_u32_e32 v50, s20, v0
	v_ashrrev_i32_e32 v51, 31, v50
	v_lshl_add_u64 v[50:51], v[50:51], 2, s[8:9]
	global_store_dword v[50:51], v62, off
	v_add_u32_e32 v50, s21, v0
	v_ashrrev_i32_e32 v51, 31, v50
	v_lshl_add_u64 v[50:51], v[50:51], 2, s[8:9]
	global_store_dword v[50:51], v63, off
	v_add_u32_e32 v50, s22, v0
	v_ashrrev_i32_e32 v51, 31, v50
	v_lshl_add_u64 v[50:51], v[50:51], 2, s[8:9]
	global_store_dword v[50:51], v64, off
	v_add_u32_e32 v50, s23, v0
	v_ashrrev_i32_e32 v51, 31, v50
	v_lshl_add_u64 v[50:51], v[50:51], 2, s[8:9]
	v_or_b32_e32 v52, 32, v0
	global_store_dword v[50:51], v65, off
	v_add_u32_e32 v50, s2, v52
	v_ashrrev_i32_e32 v51, 31, v50
	v_lshl_add_u64 v[50:51], v[50:51], 2, s[8:9]
	global_store_dword v[50:51], v34, off
	v_add_u32_e32 v50, s3, v52
	v_ashrrev_i32_e32 v51, 31, v50
	v_lshl_add_u64 v[50:51], v[50:51], 2, s[8:9]
	v_add_u32_e32 v34, s5, v52
	global_store_dword v[50:51], v35, off
	v_ashrrev_i32_e32 v35, 31, v34
	v_lshl_add_u64 v[34:35], v[34:35], 2, s[8:9]
	global_store_dword v[34:35], v36, off
	v_add_u32_e32 v34, s7, v52
	v_ashrrev_i32_e32 v35, 31, v34
	v_lshl_add_u64 v[34:35], v[34:35], 2, s[8:9]
	global_store_dword v[34:35], v37, off
	v_add_u32_e32 v34, s10, v52
	v_ashrrev_i32_e32 v35, 31, v34
	v_lshl_add_u64 v[34:35], v[34:35], 2, s[8:9]
	global_store_dword v[34:35], v38, off
	v_add_u32_e32 v34, s11, v52
	v_ashrrev_i32_e32 v35, 31, v34
	v_lshl_add_u64 v[34:35], v[34:35], 2, s[8:9]
	global_store_dword v[34:35], v39, off
	v_add_u32_e32 v34, s12, v52
	v_ashrrev_i32_e32 v35, 31, v34
	v_lshl_add_u64 v[34:35], v[34:35], 2, s[8:9]
	global_store_dword v[34:35], v40, off
	v_add_u32_e32 v34, s13, v52
	v_ashrrev_i32_e32 v35, 31, v34
	v_lshl_add_u64 v[34:35], v[34:35], 2, s[8:9]
	global_store_dword v[34:35], v41, off
	v_add_u32_e32 v34, s14, v52
	v_ashrrev_i32_e32 v35, 31, v34
	v_lshl_add_u64 v[34:35], v[34:35], 2, s[8:9]
	global_store_dword v[34:35], v42, off
	v_add_u32_e32 v34, s15, v52
	v_ashrrev_i32_e32 v35, 31, v34
	v_lshl_add_u64 v[34:35], v[34:35], 2, s[8:9]
	global_store_dword v[34:35], v43, off
	v_add_u32_e32 v34, s18, v52
	v_ashrrev_i32_e32 v35, 31, v34
	v_lshl_add_u64 v[34:35], v[34:35], 2, s[8:9]
	global_store_dword v[34:35], v44, off
	v_add_u32_e32 v34, s19, v52
	v_ashrrev_i32_e32 v35, 31, v34
	v_lshl_add_u64 v[34:35], v[34:35], 2, s[8:9]
	global_store_dword v[34:35], v45, off
	v_add_u32_e32 v34, s20, v52
	v_ashrrev_i32_e32 v35, 31, v34
	v_lshl_add_u64 v[34:35], v[34:35], 2, s[8:9]
	global_store_dword v[34:35], v46, off
	v_add_u32_e32 v34, s21, v52
	v_ashrrev_i32_e32 v35, 31, v34
	v_lshl_add_u64 v[34:35], v[34:35], 2, s[8:9]
	global_store_dword v[34:35], v47, off
	v_add_u32_e32 v34, s22, v52
	v_ashrrev_i32_e32 v35, 31, v34
	v_lshl_add_u64 v[34:35], v[34:35], 2, s[8:9]
	global_store_dword v[34:35], v48, off
	v_add_u32_e32 v34, s23, v52
	v_ashrrev_i32_e32 v35, 31, v34
	v_lshl_add_u64 v[34:35], v[34:35], 2, s[8:9]
	v_or_b32_e32 v36, 64, v0
	global_store_dword v[34:35], v49, off
	v_add_u32_e32 v34, s2, v36
	v_ashrrev_i32_e32 v35, 31, v34
	v_lshl_add_u64 v[34:35], v[34:35], 2, s[8:9]
	global_store_dword v[34:35], v18, off
	v_add_u32_e32 v34, s3, v36
	v_ashrrev_i32_e32 v35, 31, v34
	v_lshl_add_u64 v[34:35], v[34:35], 2, s[8:9]
	v_add_u32_e32 v18, s5, v36
	global_store_dword v[34:35], v19, off
	v_ashrrev_i32_e32 v19, 31, v18
	v_lshl_add_u64 v[18:19], v[18:19], 2, s[8:9]
	global_store_dword v[18:19], v20, off
	v_add_u32_e32 v18, s7, v36
	v_ashrrev_i32_e32 v19, 31, v18
	v_lshl_add_u64 v[18:19], v[18:19], 2, s[8:9]
	global_store_dword v[18:19], v21, off
	v_add_u32_e32 v18, s10, v36
	v_ashrrev_i32_e32 v19, 31, v18
	v_lshl_add_u64 v[18:19], v[18:19], 2, s[8:9]
	global_store_dword v[18:19], v22, off
	v_add_u32_e32 v18, s11, v36
	v_ashrrev_i32_e32 v19, 31, v18
	v_lshl_add_u64 v[18:19], v[18:19], 2, s[8:9]
	global_store_dword v[18:19], v23, off
	v_add_u32_e32 v18, s12, v36
	v_ashrrev_i32_e32 v19, 31, v18
	v_lshl_add_u64 v[18:19], v[18:19], 2, s[8:9]
	global_store_dword v[18:19], v24, off
	v_add_u32_e32 v18, s13, v36
	v_ashrrev_i32_e32 v19, 31, v18
	v_lshl_add_u64 v[18:19], v[18:19], 2, s[8:9]
	global_store_dword v[18:19], v25, off
	v_add_u32_e32 v18, s14, v36
	v_ashrrev_i32_e32 v19, 31, v18
	v_lshl_add_u64 v[18:19], v[18:19], 2, s[8:9]
	global_store_dword v[18:19], v26, off
	v_add_u32_e32 v18, s15, v36
	v_ashrrev_i32_e32 v19, 31, v18
	v_lshl_add_u64 v[18:19], v[18:19], 2, s[8:9]
	global_store_dword v[18:19], v27, off
	v_add_u32_e32 v18, s18, v36
	v_ashrrev_i32_e32 v19, 31, v18
	v_lshl_add_u64 v[18:19], v[18:19], 2, s[8:9]
	global_store_dword v[18:19], v28, off
	v_add_u32_e32 v18, s19, v36
	v_ashrrev_i32_e32 v19, 31, v18
	v_lshl_add_u64 v[18:19], v[18:19], 2, s[8:9]
	global_store_dword v[18:19], v29, off
	v_add_u32_e32 v18, s20, v36
	v_ashrrev_i32_e32 v19, 31, v18
	v_lshl_add_u64 v[18:19], v[18:19], 2, s[8:9]
	global_store_dword v[18:19], v30, off
	v_add_u32_e32 v18, s21, v36
	v_ashrrev_i32_e32 v19, 31, v18
	v_lshl_add_u64 v[18:19], v[18:19], 2, s[8:9]
	global_store_dword v[18:19], v31, off
	v_add_u32_e32 v18, s22, v36
	v_ashrrev_i32_e32 v19, 31, v18
	v_lshl_add_u64 v[18:19], v[18:19], 2, s[8:9]
	global_store_dword v[18:19], v32, off
	v_add_u32_e32 v18, s23, v36
	v_ashrrev_i32_e32 v19, 31, v18
	v_lshl_add_u64 v[18:19], v[18:19], 2, s[8:9]
	v_or_b32_e32 v0, 0x60, v0
	global_store_dword v[18:19], v33, off
	v_add_u32_e32 v18, s2, v0
	v_ashrrev_i32_e32 v19, 31, v18
	v_lshl_add_u64 v[18:19], v[18:19], 2, s[8:9]
	global_store_dword v[18:19], v2, off
	v_add_u32_e32 v18, s3, v0
	v_ashrrev_i32_e32 v19, 31, v18
	v_lshl_add_u64 v[18:19], v[18:19], 2, s[8:9]
	v_add_u32_e32 v2, s5, v0
	global_store_dword v[18:19], v3, off
	v_ashrrev_i32_e32 v3, 31, v2
	v_lshl_add_u64 v[2:3], v[2:3], 2, s[8:9]
	global_store_dword v[2:3], v4, off
	v_add_u32_e32 v2, s7, v0
	v_ashrrev_i32_e32 v3, 31, v2
	v_lshl_add_u64 v[2:3], v[2:3], 2, s[8:9]
	global_store_dword v[2:3], v5, off
	v_add_u32_e32 v2, s10, v0
	v_ashrrev_i32_e32 v3, 31, v2
	v_lshl_add_u64 v[2:3], v[2:3], 2, s[8:9]
	global_store_dword v[2:3], v6, off
	v_add_u32_e32 v2, s11, v0
	v_ashrrev_i32_e32 v3, 31, v2
	v_lshl_add_u64 v[2:3], v[2:3], 2, s[8:9]
	global_store_dword v[2:3], v7, off
	v_add_u32_e32 v2, s12, v0
	v_ashrrev_i32_e32 v3, 31, v2
	v_lshl_add_u64 v[2:3], v[2:3], 2, s[8:9]
	global_store_dword v[2:3], v8, off
	v_add_u32_e32 v2, s13, v0
	v_ashrrev_i32_e32 v3, 31, v2
	v_lshl_add_u64 v[2:3], v[2:3], 2, s[8:9]
	global_store_dword v[2:3], v9, off
	v_add_u32_e32 v2, s14, v0
	v_ashrrev_i32_e32 v3, 31, v2
	v_lshl_add_u64 v[2:3], v[2:3], 2, s[8:9]
	global_store_dword v[2:3], v10, off
	v_add_u32_e32 v2, s15, v0
	v_ashrrev_i32_e32 v3, 31, v2
	v_lshl_add_u64 v[2:3], v[2:3], 2, s[8:9]
	global_store_dword v[2:3], v11, off
	v_add_u32_e32 v2, s18, v0
	v_ashrrev_i32_e32 v3, 31, v2
	v_lshl_add_u64 v[2:3], v[2:3], 2, s[8:9]
	global_store_dword v[2:3], v12, off
	v_add_u32_e32 v2, s19, v0
	v_ashrrev_i32_e32 v3, 31, v2
	v_lshl_add_u64 v[2:3], v[2:3], 2, s[8:9]
	global_store_dword v[2:3], v13, off
	v_add_u32_e32 v2, s20, v0
	v_ashrrev_i32_e32 v3, 31, v2
	v_lshl_add_u64 v[2:3], v[2:3], 2, s[8:9]
	global_store_dword v[2:3], v14, off
	v_add_u32_e32 v2, s21, v0
	v_ashrrev_i32_e32 v3, 31, v2
	v_lshl_add_u64 v[2:3], v[2:3], 2, s[8:9]
	global_store_dword v[2:3], v15, off
	v_add_u32_e32 v2, s22, v0
	v_ashrrev_i32_e32 v3, 31, v2
	v_lshl_add_u64 v[2:3], v[2:3], 2, s[8:9]
	global_store_dword v[2:3], v16, off
	v_add_u32_e32 v2, s23, v0
	v_ashrrev_i32_e32 v3, 31, v2
	v_lshl_add_u64 v[2:3], v[2:3], 2, s[8:9]
	global_store_dword v[2:3], v17, off
	s_waitcnt vmcnt(63) expcnt(7) lgkmcnt(15)
	s_barrier
	s_cbranch_execnz .LBB0_346
	s_branch .LBB0_350

.LBB0_476:
	s_and_b32 s0, s4, 3
	s_or_b32 s80, s0, s1
	v_readlane_b32 s8, v253, 0
	s_ashr_i32 s6, s4, 2
	s_lshl_b64 s[2:3], s[80:81], 2
	v_readlane_b32 s20, v253, 12
	v_readlane_b32 s9, v253, 1
	v_readlane_b32 s21, v253, 13
	s_add_u32 s8, s20, s2
	s_addc_u32 s9, s21, s3
	v_readlane_b32 s22, v253, 14
	v_readlane_b32 s23, v253, 15
	global_load_dword v0, v1, s[8:9]
	s_add_u32 s2, s22, s2
	s_addc_u32 s3, s23, s3
	v_readlane_b32 s13, v253, 5
	v_mov_b32_e32 v8, v195
	v_mov_b32_e32 v110, v194
	v_readlane_b32 s16, v253, 8
	v_readlane_b32 s17, v253, 9
	s_ashr_i32 s7, s6, 31
	s_lshl_b64 s[16:17], s[6:7], 7
	v_mov_b32_e32 v99, s17
	v_readlane_b32 s14, v253, 6
	v_readlane_b32 s15, v253, 7
	s_movk_i32 s5, 0x43
	v_readlane_b32 s18, v253, 10
	v_readlane_b32 s18, v255, 31
	v_readlane_b32 s10, v253, 2
	v_readlane_b32 s19, v253, 11
	v_readlane_b32 s10, v255, 28
	v_readlane_b32 s19, v255, 32
	v_readlane_b32 s11, v253, 3
	v_readlane_b32 s11, v255, 29
	v_readlane_b32 s20, v255, 33
	v_readlane_b32 s12, v253, 4
	v_readlane_b32 s12, v255, 30
	v_readlane_b32 s21, v255, 34
	s_waitcnt vmcnt(0)
	v_mul_f32_e32 v0, 0x3fb8aa3b, v0
	v_exp_f32_e32 v0, v0
	s_nop 0
	v_mul_f32_e32 v52, 0xbfb8aa3b, v0
	global_load_dword v0, v1, s[2:3]
	v_readfirstlane_b32 s2, v195
	s_lshr_b32 s8, s2, 6
	s_lshl_b32 s13, s8, 5
	s_and_b32 s3, s13, 0x60
	v_and_b32_e32 v109, 31, v110
	v_or_b32_e32 v54, s3, v109
	s_mul_i32 s3, s0, 0x600000
	v_ashrrev_i32_e32 v53, 5, v110
	v_or_b32_e32 v98, s16, v54
	s_add_u32 s42, s63, s3
	v_readlane_b32 s3, v255, 51
	s_addc_u32 s43, s3, 0
	v_lshlrev_b64 v[2:3], 8, v[98:99]
	v_lshlrev_b32_e32 v50, 3, v53
	v_lshl_add_u64 v[2:3], s[42:43], 0, v[2:3]
	v_ashrrev_i32_e32 v51, 31, v50
	v_lshl_add_u64 v[2:3], v[50:51], 1, v[2:3]
	s_mov_b64 s[16:17], 0x12000000
	s_mov_b32 s3, 0x12000000
	s_lshl_b64 s[14:15], s[6:7], 15
	v_lshl_add_u64 v[4:5], v[2:3], 0, s[16:17]
	v_add_co_u32_e32 v2, vcc, s3, v2
	s_add_u32 s14, s42, s14
	v_and_b32_e32 v11, 15, v8
	v_addc_co_u32_e32 v3, vcc, 0, v3, vcc
	s_addc_u32 s15, s43, s15
	global_load_dwordx4 v[94:97], v[2:3], off
	global_load_dwordx4 v[90:93], v[4:5], off offset:32
	global_load_dwordx4 v[86:89], v[4:5], off offset:64
	global_load_dwordx4 v[82:85], v[4:5], off offset:96
	global_load_dwordx4 v[78:81], v[4:5], off offset:128
	global_load_dwordx4 v[74:77], v[4:5], off offset:160
	global_load_dwordx4 v[70:73], v[4:5], off offset:192
	global_load_dwordx4 v[66:69], v[4:5], off offset:224
	v_ashrrev_i32_e32 v8, 4, v8
	v_bfe_u32 v18, v8, 2, 2
	v_ashrrev_i32_e32 v9, 31, v8
	s_add_i32 s9, 0, 0x10000
	s_mov_b32 s3, 0x8000
	v_bfe_u32 v51, v110, 2, 2
	v_lshlrev_b32_e32 v111, 2, v53
	v_add_u32_e32 v23, 8, v111
	v_and_b32_e32 v38, 3, v53
	v_lshlrev_b32_e32 v112, 2, v51
	v_bfe_u32 v40, v23, 2, 2
	v_lshl_add_u32 v22, v109, 8, 0
	v_sub_u32_e32 v61, v54, v111
	v_cmp_gt_i32_e64 s[38:39], 0, v61
	v_sub_u32_e32 v62, v54, v23
	v_subrev_u32_e32 v105, 32, v61
	v_subrev_u32_e32 v107, 33, v61
	v_cvt_f32_i32_e32 v105, v105
	v_cvt_f32_i32_e32 v107, v107
	s_movk_i32 s6, 0x63
	s_add_i32 s16, 0, 0x12000
	v_mul_f32_e32 v106, v52, v105
	v_mul_f32_e32 v108, v52, v107
	v_exp_f32_e32 v106, v106
	v_exp_f32_e32 v108, v108
	s_add_i32 s17, 0, 0x1a000
	s_add_i32 s7, 0, 0x14000
	s_waitcnt vmcnt(8)
	v_mul_f32_e32 v0, 0x3fb8aa3b, v0
	v_exp_f32_e32 v10, v0
	v_lshlrev_b32_e32 v0, 4, v11
	v_lshl_add_u64 v[2:3], s[14:15], 0, v[0:1]
	s_mov_b64 s[14:15], 0x13800000
	v_lshl_add_u64 v[6:7], v[2:3], 0, s[14:15]
	s_mov_b64 s[14:15], 0x15000000
	v_lshl_add_u64 v[4:5], v[2:3], 0, s[14:15]
	v_lshlrev_b32_e32 v3, 2, v8
	v_and_b32_e32 v3, 12, v3
	v_lshlrev_b32_e32 v2, 8, v8
	v_bitop3_b32 v3, v3, v11, v18 bitop3:0x36
	v_lshl_or_b32 v16, v3, 4, v2
	v_lshlrev_b64 v[2:3], 8, v[8:9]
	v_lshl_add_u64 v[184:185], v[6:7], 0, v[2:3]
	v_lshl_add_u64 v[186:187], v[4:5], 0, v[2:3]
	v_or_b32_e32 v188, v2, v0
	v_mov_b32_e32 v189, v3
	v_lshl_add_u64 v[188:189], s[40:41], 0, v[188:189]
	v_add_co_u32_e32 v190, vcc, 0x8000, v188
	s_nop 1
	v_addc_co_u32_e32 v191, vcc, 0, v189, vcc
	global_load_dwordx4 v[120:123], v[184:185], off
	global_load_dwordx4 v[124:127], v[186:187], off
	global_load_dwordx4 v[128:131], v[188:189], off
	global_load_dwordx4 v[132:135], v[190:191], off
	v_add_co_u32_e32 v184, vcc, 0x2000, v184
	s_nop 1
	v_addc_co_u32_e32 v185, vcc, 0, v185, vcc
	v_add_co_u32_e32 v186, vcc, 0x2000, v186
	s_nop 1
	v_addc_co_u32_e32 v187, vcc, 0, v187, vcc
	v_add_co_u32_e32 v188, vcc, 0x2000, v188
	s_nop 1
	v_addc_co_u32_e32 v189, vcc, 0, v189, vcc
	v_add_co_u32_e32 v190, vcc, 0x2000, v190
	s_nop 1
	v_addc_co_u32_e32 v191, vcc, 0, v191, vcc
	global_load_dwordx4 v[136:139], v[184:185], off
	global_load_dwordx4 v[140:143], v[186:187], off
	global_load_dwordx4 v[144:147], v[188:189], off
	global_load_dwordx4 v[148:151], v[190:191], off
	v_add_co_u32_e32 v184, vcc, 0x2000, v184
	s_nop 1
	v_addc_co_u32_e32 v185, vcc, 0, v185, vcc
	v_add_co_u32_e32 v186, vcc, 0x2000, v186
	s_nop 1
	v_addc_co_u32_e32 v187, vcc, 0, v187, vcc
	v_add_co_u32_e32 v188, vcc, 0x2000, v188
	s_nop 1
	v_addc_co_u32_e32 v189, vcc, 0, v189, vcc
	v_add_co_u32_e32 v190, vcc, 0x2000, v190
	s_nop 1
	v_addc_co_u32_e32 v191, vcc, 0, v191, vcc
	global_load_dwordx4 v[152:155], v[184:185], off
	global_load_dwordx4 v[156:159], v[186:187], off
	global_load_dwordx4 v[160:163], v[188:189], off
	global_load_dwordx4 v[164:167], v[190:191], off
	v_add_co_u32_e32 v184, vcc, 0x2000, v184
	s_nop 1
	v_addc_co_u32_e32 v185, vcc, 0, v185, vcc
	v_add_co_u32_e32 v186, vcc, 0x2000, v186
	s_nop 1
	v_addc_co_u32_e32 v187, vcc, 0, v187, vcc
	v_add_co_u32_e32 v188, vcc, 0x2000, v188
	s_nop 1
	v_addc_co_u32_e32 v189, vcc, 0, v189, vcc
	v_add_co_u32_e32 v190, vcc, 0x2000, v190
	s_nop 1
	v_addc_co_u32_e32 v191, vcc, 0, v191, vcc
	global_load_dwordx4 v[168:171], v[184:185], off
	global_load_dwordx4 v[172:175], v[186:187], off
	global_load_dwordx4 v[176:179], v[188:189], off
	global_load_dwordx4 v[180:183], v[190:191], off
	v_lshl_add_u64 v[12:13], v[6:7], 0, v[2:3]
	v_add_u32_e32 v9, 0, v16
	s_add_i32 s14, 0, 0x18000
	s_lshr_b32 s15, s2, 8
	s_lshl_b32 s2, s15, 3
	v_mul_f32_e32 v57, 0x3fb8aa3b, v10
	v_mul_f32_e32 v105, v57, v105
	v_mul_f32_e32 v107, v57, v107
	v_exp_f32_e32 v105, v105
	v_exp_f32_e32 v107, v107
	s_waitcnt vmcnt(15)
	v_mov_b32_e32 v12, v120
	v_mov_b32_e32 v13, v121
	v_mov_b32_e32 v14, v122
	v_mov_b32_e32 v15, v123
	ds_write_b128 v9, v[12:15]
	v_lshl_add_u64 v[12:13], v[4:5], 0, v[2:3]
	v_or_b32_e32 v2, v2, v0
	v_lshl_add_u64 v[2:3], s[40:41], 0, v[2:3]
	v_add_u32_e32 v0, s9, v16
	s_waitcnt vmcnt(14)
	v_mov_b32_e32 v12, v124
	v_mov_b32_e32 v13, v125
	v_mov_b32_e32 v14, v126
	v_mov_b32_e32 v15, v127
	ds_write_b128 v9, v[12:15] offset:32768
	s_waitcnt vmcnt(13)
	v_mov_b32_e32 v12, v128
	v_mov_b32_e32 v13, v129
	v_mov_b32_e32 v14, v130
	v_mov_b32_e32 v15, v131
	ds_write_b128 v0, v[12:15]
	v_add_co_u32_e32 v12, vcc, s3, v2
	v_add_u32_e32 v0, s14, v16
	s_nop 0
	v_addc_co_u32_e32 v13, vcc, 0, v3, vcc
	s_movk_i32 s3, 0x2000
	s_waitcnt vmcnt(12)
	v_mov_b32_e32 v12, v132
	v_mov_b32_e32 v13, v133
	v_mov_b32_e32 v14, v134
	v_mov_b32_e32 v15, v135
	ds_write_b128 v0, v[12:15]
	v_add_u32_e32 v12, 32, v8
	v_ashrrev_i32_e32 v13, 31, v12
	v_lshlrev_b64 v[16:17], 8, v[12:13]
	v_lshlrev_b32_e32 v0, 8, v12
	v_lshlrev_b32_e32 v9, 2, v12
	v_lshl_add_u64 v[12:13], v[6:7], 0, v[16:17]
	v_and_b32_e32 v9, 12, v9
	v_bitop3_b32 v9, v9, v11, v18 bitop3:0x36
	v_lshl_or_b32 v0, v9, 4, v0
	v_add_u32_e32 v9, 0, v0
	s_waitcnt vmcnt(11)
	v_mov_b32_e32 v12, v136
	v_mov_b32_e32 v13, v137
	v_mov_b32_e32 v14, v138
	v_mov_b32_e32 v15, v139
	ds_write_b128 v9, v[12:15]
	v_lshl_add_u64 v[12:13], v[4:5], 0, v[16:17]
	s_waitcnt vmcnt(10)
	v_mov_b32_e32 v12, v140
	v_mov_b32_e32 v13, v141
	v_mov_b32_e32 v14, v142
	v_mov_b32_e32 v15, v143
	ds_write_b128 v9, v[12:15] offset:32768
	v_add_co_u32_e32 v12, vcc, s3, v2
	v_add_u32_e32 v9, s9, v0
	s_nop 0
	v_addc_co_u32_e32 v13, vcc, 0, v3, vcc
	s_mov_b32 s3, 0xa000
	v_add_u32_e32 v0, s14, v0
	s_waitcnt vmcnt(9)
	v_mov_b32_e32 v12, v144
	v_mov_b32_e32 v13, v145
	v_mov_b32_e32 v14, v146
	v_mov_b32_e32 v15, v147
	ds_write_b128 v9, v[12:15]
	v_add_co_u32_e32 v12, vcc, s3, v2
	s_movk_i32 s3, 0x4000
	s_nop 0
	v_addc_co_u32_e32 v13, vcc, 0, v3, vcc
	s_waitcnt vmcnt(8)
	v_mov_b32_e32 v12, v148
	v_mov_b32_e32 v13, v149
	v_mov_b32_e32 v14, v150
	v_mov_b32_e32 v15, v151
	ds_write_b128 v0, v[12:15]
	v_add_u32_e32 v12, 64, v8
	v_ashrrev_i32_e32 v13, 31, v12
	v_lshlrev_b64 v[16:17], 8, v[12:13]
	v_lshlrev_b32_e32 v0, 8, v12
	v_lshlrev_b32_e32 v9, 2, v12
	v_lshl_add_u64 v[12:13], v[6:7], 0, v[16:17]
	v_and_b32_e32 v9, 12, v9
	v_bitop3_b32 v9, v9, v11, v18 bitop3:0x36
	v_lshl_or_b32 v0, v9, 4, v0
	v_add_u32_e32 v9, 0, v0
	v_add_u32_e32 v8, 0x60, v8
	s_waitcnt vmcnt(7)
	v_mov_b32_e32 v12, v152
	v_mov_b32_e32 v13, v153
	v_mov_b32_e32 v14, v154
	v_mov_b32_e32 v15, v155
	ds_write_b128 v9, v[12:15]
	v_lshl_add_u64 v[12:13], v[4:5], 0, v[16:17]
	s_waitcnt vmcnt(6)
	v_mov_b32_e32 v12, v156
	v_mov_b32_e32 v13, v157
	v_mov_b32_e32 v14, v158
	v_mov_b32_e32 v15, v159
	ds_write_b128 v9, v[12:15] offset:32768
	v_add_co_u32_e32 v12, vcc, s3, v2
	v_add_u32_e32 v9, s9, v0
	s_nop 0
	v_addc_co_u32_e32 v13, vcc, 0, v3, vcc
	s_mov_b32 s3, 0xc000
	v_add_u32_e32 v0, s14, v0
	s_waitcnt vmcnt(5)
	v_mov_b32_e32 v12, v160
	v_mov_b32_e32 v13, v161
	v_mov_b32_e32 v14, v162
	v_mov_b32_e32 v15, v163
	ds_write_b128 v9, v[12:15]
	v_add_co_u32_e32 v12, vcc, s3, v2
	v_lshlrev_b32_e32 v9, 2, v8
	s_nop 0
	v_addc_co_u32_e32 v13, vcc, 0, v3, vcc
	v_and_b32_e32 v9, 12, v9
	v_bitop3_b32 v9, v9, v11, v18 bitop3:0x36
	s_movk_i32 s3, 0x6000
	v_add_u32_e32 v18, 2, v53
	s_waitcnt vmcnt(4)
	v_mov_b32_e32 v12, v164
	v_mov_b32_e32 v13, v165
	v_mov_b32_e32 v14, v166
	v_mov_b32_e32 v15, v167
	ds_write_b128 v0, v[12:15]
	v_lshlrev_b32_e32 v0, 8, v8
	v_lshl_or_b32 v0, v9, 4, v0
	v_ashrrev_i32_e32 v9, 31, v8
	v_lshlrev_b64 v[12:13], 8, v[8:9]
	v_lshl_add_u64 v[6:7], v[6:7], 0, v[12:13]
	v_add_u32_e32 v11, 0, v0
	v_lshl_add_u64 v[4:5], v[4:5], 0, v[12:13]
	s_waitcnt vmcnt(3)
	v_mov_b32_e32 v6, v168
	v_mov_b32_e32 v7, v169
	v_mov_b32_e32 v8, v170
	v_mov_b32_e32 v9, v171
	ds_write_b128 v11, v[6:9]
	v_add_u32_e32 v8, s9, v0
	v_add_u32_e32 v0, s14, v0
	s_waitcnt vmcnt(2)
	v_mov_b32_e32 v4, v172
	v_mov_b32_e32 v5, v173
	v_mov_b32_e32 v6, v174
	v_mov_b32_e32 v7, v175
	ds_write_b128 v11, v[4:7] offset:32768
	v_add_co_u32_e32 v4, vcc, s3, v2
	s_mov_b32 s3, 0xe000
	s_nop 0
	v_addc_co_u32_e32 v5, vcc, 0, v3, vcc
	v_add_co_u32_e32 v2, vcc, s3, v2
	s_movk_i32 s3, 0x42
	s_nop 0
	v_addc_co_u32_e32 v3, vcc, 0, v3, vcc
	v_cmp_gt_i32_e32 vcc, 1, v61
	s_waitcnt vmcnt(1)
	v_mov_b32_e32 v4, v176
	v_mov_b32_e32 v5, v177
	v_mov_b32_e32 v6, v178
	v_mov_b32_e32 v7, v179
	ds_write_b128 v8, v[4:7]
	s_waitcnt vmcnt(0)
	v_mov_b32_e32 v2, v180
	v_mov_b32_e32 v3, v181
	v_mov_b32_e32 v4, v182
	v_mov_b32_e32 v5, v183
	ds_write_b128 v0, v[2:5]
	v_lshrrev_b32_e32 v3, 3, v110
	v_and_b32_e32 v3, 2, v3
	v_bfe_u32 v4, v110, 1, 1
	v_or3_b32 v55, v3, s2, v4
	v_lshlrev_b32_e32 v3, 3, v110
	v_or_b32_e32 v2, v111, v51
	v_and_b32_e32 v56, 8, v3
	v_lshl_or_b32 v39, v2, 8, v56
	v_or_b32_e32 v2, v23, v51
	v_lshlrev_b32_e32 v0, 2, v110
	v_lshl_or_b32 v41, v2, 8, v56
	v_bitop3_b32 v2, v112, v55, v38 bitop3:0x36
	v_and_b32_e32 v0, 12, v0
	v_lshlrev_b32_e32 v24, 4, v2
	v_bitop3_b32 v2, v112, v55, v40 bitop3:0x36
	v_lshlrev_b32_e32 v25, 4, v2
	v_bitop3_b32 v2, v0, v53, v51 bitop3:0x36
	v_lshl_add_u32 v102, v2, 4, v22
	s_waitcnt lgkmcnt(0)
	s_barrier
	ds_read_b128 v[2:5], v102
	v_bitop3_b32 v18, v0, v18, v51 bitop3:0x36
	v_lshl_add_u32 v104, v18, 4, v22
	ds_read_b128 v[18:21], v104
	s_waitcnt lgkmcnt(1)
	v_mfma_f32_32x32x16_bf16 v[2:17], v[2:5], v[94:97], 0
	v_add3_u32 v60, v24, v39, 0
	v_add3_u32 v59, v25, v41, 0
	v_or_b32_e32 v113, 4, v55
	s_movk_i32 s2, 0x41
	s_waitcnt lgkmcnt(0)
	v_mfma_f32_32x32x16_bf16 v[2:17], v[18:21], v[90:93], v[2:17]
	v_add_u32_e32 v18, 4, v53
	v_bitop3_b32 v18, v0, v18, v51 bitop3:0x36
	v_lshl_add_u32 v103, v18, 4, v22
	ds_read_b128 v[18:21], v103
	s_waitcnt lgkmcnt(0)
	v_mfma_f32_32x32x16_bf16 v[2:17], v[18:21], v[86:89], v[2:17]
	v_add_u32_e32 v18, 6, v53
	v_bitop3_b32 v18, v0, v18, v51 bitop3:0x36
	v_lshl_add_u32 v101, v18, 4, v22
	ds_read_b128 v[18:21], v101
	s_waitcnt lgkmcnt(0)
	v_mfma_f32_32x32x16_bf16 v[2:17], v[18:21], v[82:85], v[2:17]
	v_add_u32_e32 v18, 8, v53
	v_bitop3_b32 v18, v0, v18, v51 bitop3:0x36
	v_lshl_add_u32 v100, v18, 4, v22
	ds_read_b128 v[18:21], v100
	s_waitcnt lgkmcnt(0)
	v_mfma_f32_32x32x16_bf16 v[2:17], v[18:21], v[78:81], v[2:17]
	v_add_u32_e32 v18, 10, v53
	v_bitop3_b32 v18, v0, v18, v51 bitop3:0x36
	v_lshl_add_u32 v65, v18, 4, v22
	ds_read_b128 v[18:21], v65
	s_waitcnt lgkmcnt(0)
	v_mfma_f32_32x32x16_bf16 v[2:17], v[18:21], v[74:77], v[2:17]
	v_add_u32_e32 v18, 12, v53
	v_bitop3_b32 v18, v0, v18, v51 bitop3:0x36
	v_lshl_add_u32 v64, v18, 4, v22
	ds_read_b128 v[18:21], v64
	s_waitcnt lgkmcnt(0)
	v_mfma_f32_32x32x16_bf16 v[2:17], v[18:21], v[70:73], v[2:17]
	v_add_u32_e32 v18, 14, v53
	v_bitop3_b32 v0, v0, v18, v51 bitop3:0x36
	v_lshl_add_u32 v63, v0, 4, v22
	ds_read_b128 v[18:21], v63
	v_cvt_f32_i32_e32 v0, v61
	s_waitcnt lgkmcnt(0)
	v_mfma_f32_32x32x16_bf16 v[2:17], v[18:21], v[66:69], v[2:17]
	v_add_u32_e32 v19, -1, v61
	v_cvt_f32_i32_e32 v19, v19
	v_mul_f32_e32 v18, v52, v0
	v_mul_f32_e32 v0, v57, v0
	v_exp_f32_e32 v18, v18
	v_mul_f32_e32 v20, v52, v19
	v_mul_f32_e32 v19, v57, v19
	v_exp_f32_e32 v0, v0
	v_exp_f32_e32 v20, v20
	v_exp_f32_e32 v19, v19
	v_cndmask_b32_e64 v18, v18, v0, s[38:39]
	v_add_u32_e32 v0, -2, v61
	v_cndmask_b32_e32 v19, v20, v19, vcc
	v_pk_mul_f32 v[18:19], v[18:19], s[64:65] op_sel_hi:[1,0]
	v_cvt_f32_i32_e32 v0, v0
	v_pk_mul_f32 v[2:3], v[18:19], v[2:3]
	v_add_u32_e32 v19, -3, v61
	v_cvt_f32_i32_e32 v19, v19
	v_mul_f32_e32 v18, v52, v0
	v_mul_f32_e32 v0, v57, v0
	v_exp_f32_e32 v18, v18
	v_mul_f32_e32 v20, v52, v19
	v_mul_f32_e32 v19, v57, v19
	v_exp_f32_e32 v0, v0
	v_exp_f32_e32 v20, v20
	v_exp_f32_e32 v19, v19
	v_cmp_gt_i32_e32 vcc, 2, v61
	v_cmp_gt_i32_e64 s[38:39], 3, v61
	v_cvt_pk_bf16_f32 v2, v2, v3
	v_cndmask_b32_e32 v18, v18, v0, vcc
	v_cndmask_b32_e64 v19, v20, v19, s[38:39]
	v_pk_mul_f32 v[18:19], v[18:19], s[64:65] op_sel_hi:[1,0]
	v_cvt_f32_i32_e32 v0, v62
	v_pk_mul_f32 v[4:5], v[18:19], v[4:5]
	v_add_u32_e32 v19, -1, v62
	v_cvt_f32_i32_e32 v19, v19
	v_mul_f32_e32 v18, v52, v0
	v_mul_f32_e32 v0, v57, v0
	v_exp_f32_e32 v18, v18
	v_mul_f32_e32 v20, v52, v19
	v_mul_f32_e32 v19, v57, v19
	v_exp_f32_e32 v0, v0
	v_exp_f32_e32 v20, v20
	v_exp_f32_e32 v19, v19
	v_cmp_gt_i32_e32 vcc, 1, v62
	v_cmp_gt_i32_e64 s[38:39], 0, v62
	v_cvt_pk_bf16_f32 v3, v4, v5
	v_cndmask_b32_e32 v19, v20, v19, vcc
	v_cndmask_b32_e64 v18, v18, v0, s[38:39]
	v_pk_mul_f32 v[18:19], v[18:19], s[64:65] op_sel_hi:[1,0]
	v_add_u32_e32 v0, -2, v62
	v_pk_mul_f32 v[6:7], v[18:19], v[6:7]
	v_add_u32_e32 v19, -3, v62
	v_cvt_f32_i32_e32 v0, v0
	v_cvt_f32_i32_e32 v19, v19
	v_cmp_gt_i32_e32 vcc, 2, v62
	v_cmp_gt_i32_e64 s[38:39], 3, v62
	v_mul_f32_e32 v18, v52, v0
	v_mul_f32_e32 v0, v57, v0
	v_mul_f32_e32 v20, v52, v19
	v_mul_f32_e32 v19, v57, v19
	v_exp_f32_e32 v18, v18
	v_exp_f32_e32 v0, v0
	v_exp_f32_e32 v20, v20
	v_exp_f32_e32 v19, v19
	v_cvt_pk_bf16_f32 v4, v6, v7
	v_cndmask_b32_e32 v18, v18, v0, vcc
	v_add_u32_e32 v0, -16, v61
	v_cndmask_b32_e64 v19, v20, v19, s[38:39]
	v_pk_mul_f32 v[18:19], v[18:19], s[64:65] op_sel_hi:[1,0]
	v_cvt_f32_i32_e32 v0, v0
	v_pk_mul_f32 v[8:9], v[18:19], v[8:9]
	v_subrev_u32_e32 v19, 17, v61
	v_cvt_f32_i32_e32 v19, v19
	v_mul_f32_e32 v18, v52, v0
	v_mul_f32_e32 v0, v57, v0
	v_exp_f32_e32 v18, v18
	v_mul_f32_e32 v20, v52, v19
	v_mul_f32_e32 v19, v57, v19
	v_exp_f32_e32 v0, v0
	v_exp_f32_e32 v20, v20
	v_exp_f32_e32 v19, v19
	v_cmp_gt_i32_e32 vcc, 16, v61
	v_cmp_gt_i32_e64 s[38:39], 17, v61
	ds_read_b64_tr_b16 v[6:7], v60 offset:32768
	v_cndmask_b32_e32 v18, v18, v0, vcc
	v_cndmask_b32_e64 v19, v20, v19, s[38:39]
	v_pk_mul_f32 v[18:19], v[18:19], s[64:65] op_sel_hi:[1,0]
	v_subrev_u32_e32 v0, 18, v61
	v_pk_mul_f32 v[10:11], v[18:19], v[10:11]
	v_subrev_u32_e32 v19, 19, v61
	v_cvt_f32_i32_e32 v0, v0
	v_cvt_f32_i32_e32 v19, v19
	v_cmp_gt_i32_e32 vcc, 18, v61
	v_cmp_gt_i32_e64 s[38:39], 19, v61
	v_mul_f32_e32 v18, v52, v0
	v_mul_f32_e32 v0, v57, v0
	v_mul_f32_e32 v20, v52, v19
	v_mul_f32_e32 v19, v57, v19
	v_exp_f32_e32 v18, v18
	v_exp_f32_e32 v0, v0
	v_exp_f32_e32 v20, v20
	v_exp_f32_e32 v19, v19
	v_cvt_pk_bf16_f32 v5, v8, v9
	v_cndmask_b32_e32 v18, v18, v0, vcc
	v_subrev_u32_e32 v0, 24, v61
	v_cndmask_b32_e64 v19, v20, v19, s[38:39]
	v_pk_mul_f32 v[18:19], v[18:19], s[64:65] op_sel_hi:[1,0]
	v_cvt_f32_i32_e32 v0, v0
	v_pk_mul_f32 v[12:13], v[18:19], v[12:13]
	v_subrev_u32_e32 v19, 25, v61
	v_cvt_f32_i32_e32 v19, v19
	v_mul_f32_e32 v18, v52, v0
	v_mul_f32_e32 v0, v57, v0
	v_exp_f32_e32 v18, v18
	v_mul_f32_e32 v20, v52, v19
	v_mul_f32_e32 v19, v57, v19
	v_exp_f32_e32 v0, v0
	v_exp_f32_e32 v20, v20
	v_exp_f32_e32 v19, v19
	v_cmp_gt_i32_e32 vcc, 24, v61
	v_cmp_gt_i32_e64 s[38:39], 25, v61
	v_cvt_pk_bf16_f32 v34, v10, v11
	v_cndmask_b32_e32 v18, v18, v0, vcc
	v_cndmask_b32_e64 v19, v20, v19, s[38:39]
	v_pk_mul_f32 v[18:19], v[18:19], s[64:65] op_sel_hi:[1,0]
	v_subrev_u32_e32 v0, 26, v61
	v_pk_mul_f32 v[14:15], v[18:19], v[14:15]
	v_subrev_u32_e32 v19, 27, v61
	v_cvt_f32_i32_e32 v0, v0
	v_cvt_f32_i32_e32 v19, v19
	v_cmp_gt_i32_e32 vcc, 26, v61
	v_cmp_gt_i32_e64 s[38:39], 27, v61
	v_mul_f32_e32 v18, v52, v0
	v_mul_f32_e32 v0, v57, v0
	v_mul_f32_e32 v20, v52, v19
	v_mul_f32_e32 v19, v57, v19
	v_exp_f32_e32 v18, v18
	v_exp_f32_e32 v0, v0
	v_exp_f32_e32 v20, v20
	v_exp_f32_e32 v19, v19
	v_cvt_pk_bf16_f32 v35, v12, v13
	ds_read_b64_tr_b16 v[8:9], v59 offset:32768
	ds_read_b64_tr_b16 v[10:11], v60 offset:36864
	ds_read_b64_tr_b16 v[12:13], v59 offset:36864
	v_cndmask_b32_e32 v18, v18, v0, vcc
	v_cndmask_b32_e64 v19, v20, v19, s[38:39]
	v_bitop3_b32 v0, v112, v113, v38 bitop3:0x36
	v_pk_mul_f32 v[18:19], v[18:19], s[64:65] op_sel_hi:[1,0]
	v_lshlrev_b32_e32 v0, 4, v0
	v_pk_mul_f32 v[16:17], v[18:19], v[16:17]
	s_waitcnt lgkmcnt(2)
	v_mfma_f32_32x32x16_bf16 v[18:33], v[6:9], v[2:5], 0
	v_bitop3_b32 v6, v112, v113, v40 bitop3:0x36
	v_add3_u32 v58, v0, v39, 0
	v_lshlrev_b32_e32 v8, 4, v6
	ds_read_b64_tr_b16 v[6:7], v58 offset:32768
	v_add3_u32 v0, v8, v41, 0
	ds_read_b64_tr_b16 v[8:9], v0 offset:32768
	ds_read_b64_tr_b16 v[38:39], v58 offset:36864
	ds_read_b64_tr_b16 v[40:41], v0 offset:36864
	v_cvt_pk_bf16_f32 v36, v14, v15
	v_cvt_pk_bf16_f32 v37, v16, v17
	ds_read_b128 v[114:117], v104 offset:8192
	v_cmp_gt_i32_e32 vcc, 32, v61
	s_waitcnt lgkmcnt(5)
	v_mfma_f32_32x32x16_bf16 v[18:33], v[10:13], v[34:37], v[18:33]
	v_cmp_gt_i32_e64 s[38:39], 33, v61
	v_cndmask_b32_e32 v106, v106, v105, vcc
	v_subrev_u32_e32 v105, 34, v61
	v_cndmask_b32_e64 v107, v108, v107, s[38:39]
	v_mul_f32_e64 v106, v106, s64
	v_mul_f32_e64 v107, v107, s64
	v_cvt_f32_i32_e32 v105, v105
	v_cmp_gt_i32_e32 vcc, 34, v61
	s_waitcnt lgkmcnt(3)
	v_mfma_f32_32x32x16_bf16 v[2:17], v[6:9], v[2:5], 0
	v_cmp_gt_i32_e64 s[38:39], 35, v61
	s_waitcnt lgkmcnt(1)
	v_mfma_f32_32x32x16_bf16 v[2:17], v[38:41], v[34:37], v[2:17]
	ds_read_b128 v[34:37], v102 offset:8192
	s_waitcnt lgkmcnt(0)
	v_mfma_f32_32x32x16_bf16 v[34:49], v[34:37], v[94:97], 0
	v_mfma_f32_32x32x16_bf16 v[34:49], v[114:117], v[90:93], v[34:49]
	ds_read_b128 v[114:117], v103 offset:8192
	s_waitcnt lgkmcnt(0)
	v_mfma_f32_32x32x16_bf16 v[34:49], v[114:117], v[86:89], v[34:49]
	ds_read_b128 v[114:117], v101 offset:8192
	s_waitcnt lgkmcnt(0)
	v_mfma_f32_32x32x16_bf16 v[34:49], v[114:117], v[82:85], v[34:49]
	ds_read_b128 v[114:117], v100 offset:8192
	s_waitcnt lgkmcnt(0)
	v_mfma_f32_32x32x16_bf16 v[34:49], v[114:117], v[78:81], v[34:49]
	ds_read_b128 v[114:117], v65 offset:8192
	s_waitcnt lgkmcnt(0)
	v_mfma_f32_32x32x16_bf16 v[34:49], v[114:117], v[74:77], v[34:49]
	ds_read_b128 v[114:117], v64 offset:8192
	s_waitcnt lgkmcnt(0)
	v_mfma_f32_32x32x16_bf16 v[34:49], v[114:117], v[70:73], v[34:49]
	ds_read_b128 v[114:117], v63 offset:8192
	s_waitcnt lgkmcnt(0)
	v_mfma_f32_32x32x16_bf16 v[34:49], v[114:117], v[66:69], v[34:49]
	s_nop 11
	v_pk_mul_f32 v[34:35], v[106:107], v[34:35]
	v_subrev_u32_e32 v107, 35, v61
	v_cvt_f32_i32_e32 v107, v107
	v_mul_f32_e32 v106, v52, v105
	v_mul_f32_e32 v105, v57, v105
	v_exp_f32_e32 v106, v106
	v_mul_f32_e32 v108, v52, v107
	v_mul_f32_e32 v107, v57, v107
	v_exp_f32_e32 v105, v105
	v_exp_f32_e32 v108, v108
	v_exp_f32_e32 v107, v107
	v_cvt_pk_bf16_f32 v34, v34, v35
	v_cndmask_b32_e32 v106, v106, v105, vcc
	v_subrev_u32_e32 v105, 32, v62
	v_cndmask_b32_e64 v107, v108, v107, s[38:39]
	v_pk_mul_f32 v[106:107], v[106:107], s[64:65] op_sel_hi:[1,0]
	v_cvt_f32_i32_e32 v105, v105
	v_pk_mul_f32 v[36:37], v[106:107], v[36:37]
	v_subrev_u32_e32 v107, 33, v62
	v_cvt_f32_i32_e32 v107, v107
	v_mul_f32_e32 v106, v52, v105
	v_mul_f32_e32 v105, v57, v105
	v_exp_f32_e32 v106, v106
	v_mul_f32_e32 v108, v52, v107
	v_mul_f32_e32 v107, v57, v107
	v_exp_f32_e32 v105, v105
	v_exp_f32_e32 v108, v108
	v_exp_f32_e32 v107, v107
	v_cmp_gt_i32_e32 vcc, 32, v62
	v_cmp_gt_i32_e64 s[38:39], 33, v62
	v_cvt_pk_bf16_f32 v35, v36, v37
	v_cndmask_b32_e32 v106, v106, v105, vcc
	v_cndmask_b32_e64 v107, v108, v107, s[38:39]
	v_pk_mul_f32 v[106:107], v[106:107], s[64:65] op_sel_hi:[1,0]
	v_subrev_u32_e32 v105, 34, v62
	v_pk_mul_f32 v[38:39], v[106:107], v[38:39]
	v_subrev_u32_e32 v107, 35, v62
	v_cvt_f32_i32_e32 v105, v105
	v_cvt_f32_i32_e32 v107, v107
	v_cmp_gt_i32_e32 vcc, 34, v62
	v_cmp_gt_i32_e64 s[38:39], 35, v62
	v_mul_f32_e32 v106, v52, v105
	v_mul_f32_e32 v105, v57, v105
	v_mul_f32_e32 v108, v52, v107
	v_mul_f32_e32 v107, v57, v107
	v_exp_f32_e32 v106, v106
	v_exp_f32_e32 v105, v105
	v_exp_f32_e32 v108, v108
	v_exp_f32_e32 v107, v107
	v_cvt_pk_bf16_f32 v36, v38, v39
	v_cndmask_b32_e32 v106, v106, v105, vcc
	v_subrev_u32_e32 v105, 48, v61
	v_cndmask_b32_e64 v107, v108, v107, s[38:39]
	v_pk_mul_f32 v[106:107], v[106:107], s[64:65] op_sel_hi:[1,0]
	v_cvt_f32_i32_e32 v105, v105
	v_pk_mul_f32 v[40:41], v[106:107], v[40:41]
	v_subrev_u32_e32 v107, 49, v61
	v_cvt_f32_i32_e32 v107, v107
	v_mul_f32_e32 v106, v52, v105
	v_mul_f32_e32 v105, v57, v105
	v_exp_f32_e32 v106, v106
	v_mul_f32_e32 v108, v52, v107
	v_mul_f32_e32 v107, v57, v107
	v_exp_f32_e32 v105, v105
	v_exp_f32_e32 v108, v108
	v_exp_f32_e32 v107, v107
	v_cmp_gt_i32_e32 vcc, 48, v61
	v_cmp_gt_i32_e64 s[38:39], 49, v61
	v_cvt_pk_bf16_f32 v37, v40, v41
	v_cndmask_b32_e32 v106, v106, v105, vcc
	v_cndmask_b32_e64 v107, v108, v107, s[38:39]
	v_pk_mul_f32 v[106:107], v[106:107], s[64:65] op_sel_hi:[1,0]
	v_subrev_u32_e32 v105, 50, v61
	v_pk_mul_f32 v[42:43], v[106:107], v[42:43]
	v_subrev_u32_e32 v107, 51, v61
	v_cvt_f32_i32_e32 v105, v105
	v_cvt_f32_i32_e32 v107, v107
	v_cmp_gt_i32_e32 vcc, 50, v61
	v_cmp_gt_i32_e64 s[38:39], 51, v61
	v_mul_f32_e32 v106, v52, v105
	v_mul_f32_e32 v105, v57, v105
	v_mul_f32_e32 v108, v52, v107
	v_mul_f32_e32 v107, v57, v107
	v_exp_f32_e32 v106, v106
	v_exp_f32_e32 v105, v105
	v_exp_f32_e32 v108, v108
	v_exp_f32_e32 v107, v107
	v_cvt_pk_bf16_f32 v38, v42, v43
	v_cndmask_b32_e32 v106, v106, v105, vcc
	v_subrev_u32_e32 v105, 56, v61
	v_cndmask_b32_e64 v107, v108, v107, s[38:39]
	v_pk_mul_f32 v[106:107], v[106:107], s[64:65] op_sel_hi:[1,0]
	v_cvt_f32_i32_e32 v105, v105
	v_pk_mul_f32 v[44:45], v[106:107], v[44:45]
	v_subrev_u32_e32 v107, 57, v61
	v_cvt_f32_i32_e32 v107, v107
	v_mul_f32_e32 v106, v52, v105
	v_mul_f32_e32 v105, v57, v105
	v_exp_f32_e32 v106, v106
	v_mul_f32_e32 v108, v52, v107
	v_mul_f32_e32 v107, v57, v107
	v_exp_f32_e32 v105, v105
	v_exp_f32_e32 v108, v108
	v_exp_f32_e32 v107, v107
	v_cmp_gt_i32_e32 vcc, 56, v61
	v_cmp_gt_i32_e64 s[38:39], 57, v61
	v_cvt_pk_bf16_f32 v39, v44, v45
	v_cndmask_b32_e32 v106, v106, v105, vcc
	v_cndmask_b32_e64 v107, v108, v107, s[38:39]
	v_pk_mul_f32 v[106:107], v[106:107], s[64:65] op_sel_hi:[1,0]
	v_subrev_u32_e32 v105, 58, v61
	v_pk_mul_f32 v[46:47], v[106:107], v[46:47]
	v_subrev_u32_e32 v107, 59, v61
	v_cvt_f32_i32_e32 v105, v105
	v_cvt_f32_i32_e32 v107, v107
	v_cmp_gt_i32_e32 vcc, 58, v61
	v_cmp_gt_i32_e64 s[38:39], 59, v61
	v_mul_f32_e32 v106, v52, v105
	v_mul_f32_e32 v105, v57, v105
	v_mul_f32_e32 v108, v52, v107
	v_mul_f32_e32 v107, v57, v107
	v_exp_f32_e32 v106, v106
	v_exp_f32_e32 v105, v105
	v_exp_f32_e32 v108, v108
	v_exp_f32_e32 v107, v107
	v_cvt_pk_bf16_f32 v40, v46, v47
	v_cndmask_b32_e32 v106, v106, v105, vcc
	v_subrev_u32_e32 v105, 64, v61
	v_cndmask_b32_e64 v107, v108, v107, s[38:39]
	v_pk_mul_f32 v[106:107], v[106:107], s[64:65] op_sel_hi:[1,0]
	v_cvt_f32_i32_e32 v105, v105
	v_pk_mul_f32 v[48:49], v[106:107], v[48:49]
	v_add_u32_e32 v107, 0xffffffbf, v61
	v_cvt_pk_bf16_f32 v41, v48, v49
	ds_read_b64_tr_b16 v[42:43], v60 offset:40960
	ds_read_b64_tr_b16 v[44:45], v59 offset:40960
	ds_read_b64_tr_b16 v[46:47], v60 offset:45056
	ds_read_b64_tr_b16 v[48:49], v59 offset:45056
	s_waitcnt lgkmcnt(2)
	v_mfma_f32_32x32x16_bf16 v[18:33], v[42:45], v[34:37], v[18:33]
	v_cvt_f32_i32_e32 v107, v107
	v_mul_f32_e32 v106, v52, v105
	v_mul_f32_e32 v105, v57, v105
	v_exp_f32_e32 v106, v106
	v_mul_f32_e32 v108, v52, v107
	v_mul_f32_e32 v107, v57, v107
	v_exp_f32_e32 v105, v105
	s_waitcnt lgkmcnt(0)
	v_mfma_f32_32x32x16_bf16 v[18:33], v[46:49], v[38:41], v[18:33]
	ds_read_b64_tr_b16 v[42:43], v58 offset:40960
	ds_read_b64_tr_b16 v[44:45], v0 offset:40960
	ds_read_b64_tr_b16 v[46:47], v58 offset:45056
	ds_read_b64_tr_b16 v[48:49], v0 offset:45056
	ds_read_b128 v[114:117], v104 offset:16384
	v_exp_f32_e32 v108, v108
	v_exp_f32_e32 v107, v107
	v_cmp_gt_i32_e32 vcc, 64, v61
	v_cmp_gt_i32_e64 s[38:39], s2, v61
	s_waitcnt lgkmcnt(3)
	v_mfma_f32_32x32x16_bf16 v[2:17], v[42:45], v[34:37], v[2:17]
	ds_read_b128 v[34:37], v102 offset:16384
	v_cndmask_b32_e64 v107, v108, v107, s[38:39]
	v_cndmask_b32_e32 v106, v106, v105, vcc
	v_mul_f32_e64 v106, v106, s64
	v_mul_f32_e64 v107, v107, s64
	v_add_u32_e32 v105, 0xffffffbe, v61
	v_cvt_f32_i32_e32 v105, v105
	v_cmp_gt_i32_e32 vcc, s3, v61
	s_waitcnt lgkmcnt(2)
	v_mfma_f32_32x32x16_bf16 v[2:17], v[46:49], v[38:41], v[2:17]
	v_cmp_gt_i32_e64 s[38:39], s5, v61
	s_waitcnt lgkmcnt(0)
	v_mfma_f32_32x32x16_bf16 v[34:49], v[34:37], v[94:97], 0
	v_mfma_f32_32x32x16_bf16 v[34:49], v[114:117], v[90:93], v[34:49]
	ds_read_b128 v[114:117], v103 offset:16384
	s_waitcnt lgkmcnt(0)
	v_mfma_f32_32x32x16_bf16 v[34:49], v[114:117], v[86:89], v[34:49]
	ds_read_b128 v[114:117], v101 offset:16384
	s_waitcnt lgkmcnt(0)
	v_mfma_f32_32x32x16_bf16 v[34:49], v[114:117], v[82:85], v[34:49]
	ds_read_b128 v[114:117], v100 offset:16384
	s_waitcnt lgkmcnt(0)
	v_mfma_f32_32x32x16_bf16 v[34:49], v[114:117], v[78:81], v[34:49]
	ds_read_b128 v[114:117], v65 offset:16384
	s_waitcnt lgkmcnt(0)
	v_mfma_f32_32x32x16_bf16 v[34:49], v[114:117], v[74:77], v[34:49]
	ds_read_b128 v[114:117], v64 offset:16384
	s_waitcnt lgkmcnt(0)
	v_mfma_f32_32x32x16_bf16 v[34:49], v[114:117], v[70:73], v[34:49]
	ds_read_b128 v[114:117], v63 offset:16384
	s_waitcnt lgkmcnt(0)
	v_mfma_f32_32x32x16_bf16 v[34:49], v[114:117], v[66:69], v[34:49]
	s_nop 11
	v_pk_mul_f32 v[34:35], v[106:107], v[34:35]
	v_add_u32_e32 v107, 0xffffffbd, v61
	v_cvt_f32_i32_e32 v107, v107
	v_mul_f32_e32 v106, v52, v105
	v_mul_f32_e32 v105, v57, v105
	v_exp_f32_e32 v106, v106
	v_mul_f32_e32 v108, v52, v107
	v_mul_f32_e32 v107, v57, v107
	v_exp_f32_e32 v105, v105
	v_exp_f32_e32 v108, v108
	v_exp_f32_e32 v107, v107
	v_cvt_pk_bf16_f32 v34, v34, v35
	v_cndmask_b32_e32 v106, v106, v105, vcc
	v_subrev_u32_e32 v105, 64, v62
	v_cndmask_b32_e64 v107, v108, v107, s[38:39]
	v_pk_mul_f32 v[106:107], v[106:107], s[64:65] op_sel_hi:[1,0]
	v_cvt_f32_i32_e32 v105, v105
	v_pk_mul_f32 v[36:37], v[106:107], v[36:37]
	v_add_u32_e32 v107, 0xffffffbf, v62
	v_cvt_f32_i32_e32 v107, v107
	v_mul_f32_e32 v106, v52, v105
	v_mul_f32_e32 v105, v57, v105
	v_exp_f32_e32 v106, v106
	v_mul_f32_e32 v108, v52, v107
	v_mul_f32_e32 v107, v57, v107
	v_exp_f32_e32 v105, v105
	v_exp_f32_e32 v108, v108
	v_exp_f32_e32 v107, v107
	v_cmp_gt_i32_e32 vcc, 64, v62
	v_cmp_gt_i32_e64 s[38:39], s2, v62
	s_movk_i32 s2, 0x50
	v_cndmask_b32_e32 v106, v106, v105, vcc
	v_cndmask_b32_e64 v107, v108, v107, s[38:39]
	v_pk_mul_f32 v[106:107], v[106:107], s[64:65] op_sel_hi:[1,0]
	v_add_u32_e32 v105, 0xffffffbe, v62
	v_pk_mul_f32 v[38:39], v[106:107], v[38:39]
	v_add_u32_e32 v107, 0xffffffbd, v62
	v_cvt_f32_i32_e32 v105, v105
	v_cvt_f32_i32_e32 v107, v107
	v_cmp_gt_i32_e32 vcc, s3, v62
	v_cmp_gt_i32_e64 s[38:39], s5, v62
	v_mul_f32_e32 v106, v52, v105
	v_mul_f32_e32 v105, v57, v105
	v_mul_f32_e32 v108, v52, v107
	v_mul_f32_e32 v107, v57, v107
	v_exp_f32_e32 v106, v106
	v_exp_f32_e32 v105, v105
	v_exp_f32_e32 v108, v108
	v_exp_f32_e32 v107, v107
	v_cvt_pk_bf16_f32 v35, v36, v37
	v_cndmask_b32_e32 v106, v106, v105, vcc
	v_add_u32_e32 v105, 0xffffffb0, v61
	v_cndmask_b32_e64 v107, v108, v107, s[38:39]
	v_pk_mul_f32 v[106:107], v[106:107], s[64:65] op_sel_hi:[1,0]
	v_cvt_f32_i32_e32 v105, v105
	v_pk_mul_f32 v[40:41], v[106:107], v[40:41]
	v_add_u32_e32 v107, 0xffffffaf, v61
	v_cvt_f32_i32_e32 v107, v107
	v_mul_f32_e32 v106, v52, v105
	v_mul_f32_e32 v105, v57, v105
	v_exp_f32_e32 v106, v106
	v_mul_f32_e32 v108, v52, v107
	v_mul_f32_e32 v107, v57, v107
	v_exp_f32_e32 v105, v105
	v_exp_f32_e32 v108, v108
	v_exp_f32_e32 v107, v107
	v_cmp_gt_i32_e32 vcc, s2, v61
	s_movk_i32 s2, 0x51
	v_cmp_gt_i32_e64 s[38:39], s2, v61
	v_cndmask_b32_e32 v106, v106, v105, vcc
	v_add_u32_e32 v105, 0xffffffae, v61
	v_cndmask_b32_e64 v107, v108, v107, s[38:39]
	v_pk_mul_f32 v[106:107], v[106:107], s[64:65] op_sel_hi:[1,0]
	v_cvt_f32_i32_e32 v105, v105
	v_pk_mul_f32 v[42:43], v[106:107], v[42:43]
	v_add_u32_e32 v107, 0xffffffad, v61
	v_cvt_f32_i32_e32 v107, v107
	v_mul_f32_e32 v106, v52, v105
	v_mul_f32_e32 v105, v57, v105
	v_exp_f32_e32 v106, v106
	v_mul_f32_e32 v108, v52, v107
	v_mul_f32_e32 v107, v57, v107
	v_exp_f32_e32 v105, v105
	v_exp_f32_e32 v108, v108
	v_exp_f32_e32 v107, v107
	s_movk_i32 s2, 0x52
	v_cmp_gt_i32_e32 vcc, s2, v61
	s_movk_i32 s2, 0x53
	v_cmp_gt_i32_e64 s[38:39], s2, v61
	v_cndmask_b32_e32 v106, v106, v105, vcc
	v_add_u32_e32 v105, 0xffffffa8, v61
	v_cndmask_b32_e64 v107, v108, v107, s[38:39]
	v_pk_mul_f32 v[106:107], v[106:107], s[64:65] op_sel_hi:[1,0]
	v_cvt_f32_i32_e32 v105, v105
	v_pk_mul_f32 v[44:45], v[106:107], v[44:45]
	v_add_u32_e32 v107, 0xffffffa7, v61
	v_cvt_f32_i32_e32 v107, v107
	v_mul_f32_e32 v106, v52, v105
	v_mul_f32_e32 v105, v57, v105
	v_exp_f32_e32 v106, v106
	v_mul_f32_e32 v108, v52, v107
	v_mul_f32_e32 v107, v57, v107
	v_exp_f32_e32 v105, v105
	v_exp_f32_e32 v108, v108
	v_exp_f32_e32 v107, v107
	s_movk_i32 s2, 0x58
	v_cmp_gt_i32_e32 vcc, s2, v61
	s_movk_i32 s2, 0x59
	v_cmp_gt_i32_e64 s[38:39], s2, v61
	v_cndmask_b32_e32 v106, v106, v105, vcc
	v_add_u32_e32 v105, 0xffffffa6, v61
	v_cndmask_b32_e64 v107, v108, v107, s[38:39]
	v_pk_mul_f32 v[106:107], v[106:107], s[64:65] op_sel_hi:[1,0]
	v_cvt_f32_i32_e32 v105, v105
	v_pk_mul_f32 v[46:47], v[106:107], v[46:47]
	v_add_u32_e32 v107, 0xffffffa5, v61
	v_cvt_f32_i32_e32 v107, v107
	v_mul_f32_e32 v106, v52, v105
	v_mul_f32_e32 v105, v57, v105
	v_exp_f32_e32 v106, v106
	v_mul_f32_e32 v108, v52, v107
	v_mul_f32_e32 v107, v57, v107
	v_exp_f32_e32 v105, v105
	v_exp_f32_e32 v108, v108
	v_exp_f32_e32 v107, v107
	s_movk_i32 s2, 0x5a
	v_cmp_gt_i32_e32 vcc, s2, v61
	s_movk_i32 s2, 0x5b
	v_cmp_gt_i32_e64 s[38:39], s2, v61
	v_cndmask_b32_e32 v106, v106, v105, vcc
	v_cvt_pk_bf16_f32 v36, v38, v39
	v_cndmask_b32_e64 v107, v108, v107, s[38:39]
	v_pk_mul_f32 v[106:107], v[106:107], s[64:65] op_sel_hi:[1,0]
	v_cvt_pk_bf16_f32 v37, v40, v41
	v_pk_mul_f32 v[48:49], v[106:107], v[48:49]
	v_cvt_pk_bf16_f32 v38, v42, v43
	v_cvt_pk_bf16_f32 v39, v44, v45
	v_cvt_pk_bf16_f32 v40, v46, v47
	v_cvt_pk_bf16_f32 v41, v48, v49
	ds_read_b64_tr_b16 v[42:43], v60 offset:49152
	ds_read_b64_tr_b16 v[44:45], v59 offset:49152
	ds_read_b64_tr_b16 v[46:47], v60 offset:53248
	ds_read_b64_tr_b16 v[48:49], v59 offset:53248
	s_waitcnt lgkmcnt(2)
	v_mfma_f32_32x32x16_bf16 v[18:33], v[42:45], v[34:37], v[18:33]
	s_movk_i32 s3, 0x60
	s_movk_i32 s2, 0x61
	v_cmp_gt_i32_e32 vcc, s3, v61
	v_cmp_gt_i32_e64 s[38:39], s2, v61
	s_movk_i32 s5, 0x62
	s_waitcnt lgkmcnt(0)
	v_mfma_f32_32x32x16_bf16 v[18:33], v[46:49], v[38:41], v[18:33]
	ds_read_b64_tr_b16 v[42:43], v58 offset:49152
	ds_read_b64_tr_b16 v[44:45], v0 offset:49152
	ds_read_b64_tr_b16 v[46:47], v58 offset:53248
	ds_read_b64_tr_b16 v[48:49], v0 offset:53248
	ds_read_b128 v[104:107], v104 offset:24576
	s_waitcnt lgkmcnt(3)
	v_mfma_f32_32x32x16_bf16 v[2:17], v[42:45], v[34:37], v[2:17]
	ds_read_b128 v[34:37], v102 offset:24576
	s_waitcnt lgkmcnt(2)
	v_mfma_f32_32x32x16_bf16 v[2:17], v[46:49], v[38:41], v[2:17]
	s_waitcnt lgkmcnt(0)
	v_mfma_f32_32x32x16_bf16 v[34:49], v[34:37], v[94:97], 0
	v_mfma_f32_32x32x16_bf16 v[34:49], v[104:107], v[90:93], v[34:49]
	ds_read_b128 v[102:105], v103 offset:24576
	s_waitcnt lgkmcnt(0)
	v_mfma_f32_32x32x16_bf16 v[34:49], v[102:105], v[86:89], v[34:49]
	ds_read_b128 v[102:105], v101 offset:24576
	s_waitcnt lgkmcnt(0)
	v_mfma_f32_32x32x16_bf16 v[34:49], v[102:105], v[82:85], v[34:49]
	ds_read_b128 v[100:103], v100 offset:24576
	s_waitcnt lgkmcnt(0)
	v_mfma_f32_32x32x16_bf16 v[34:49], v[100:103], v[78:81], v[34:49]
	ds_read_b128 v[100:103], v65 offset:24576
	v_add_u32_e32 v65, 0xffffff9f, v61
	v_cvt_f32_i32_e32 v65, v65
	s_waitcnt lgkmcnt(0)
	v_mfma_f32_32x32x16_bf16 v[34:49], v[100:103], v[74:77], v[34:49]
	ds_read_b128 v[100:103], v64 offset:24576
	s_waitcnt lgkmcnt(0)
	v_mfma_f32_32x32x16_bf16 v[34:49], v[100:103], v[70:73], v[34:49]
	ds_read_b128 v[100:103], v63 offset:24576
	v_add_u32_e32 v63, 0xffffffa0, v61
	v_cvt_f32_i32_e32 v63, v63
	v_mul_f32_e32 v64, v52, v63
	s_waitcnt lgkmcnt(0)
	v_mfma_f32_32x32x16_bf16 v[34:49], v[100:103], v[66:69], v[34:49]
	v_mul_f32_e32 v63, v57, v63
	v_mul_f32_e32 v100, v52, v65
	v_mul_f32_e32 v65, v57, v65
	v_exp_f32_e32 v64, v64
	v_exp_f32_e32 v63, v63
	v_exp_f32_e32 v100, v100
	v_exp_f32_e32 v65, v65
	v_cndmask_b32_e32 v64, v64, v63, vcc
	v_add_u32_e32 v63, 0xffffff9e, v61
	v_cndmask_b32_e64 v65, v100, v65, s[38:39]
	v_pk_mul_f32 v[64:65], v[64:65], s[64:65] op_sel_hi:[1,0]
	v_cvt_f32_i32_e32 v63, v63
	v_pk_mul_f32 v[34:35], v[64:65], v[34:35]
	v_add_u32_e32 v65, 0xffffff9d, v61
	v_cvt_f32_i32_e32 v65, v65
	v_mul_f32_e32 v64, v52, v63
	v_mul_f32_e32 v63, v57, v63
	v_exp_f32_e32 v64, v64
	v_exp_f32_e32 v63, v63
	v_mul_f32_e32 v100, v52, v65
	v_mul_f32_e32 v65, v57, v65
	v_exp_f32_e32 v100, v100
	v_exp_f32_e32 v65, v65
	v_cmp_gt_i32_e32 vcc, s5, v61
	v_cmp_gt_i32_e64 s[38:39], s6, v61
	v_cvt_pk_bf16_f32 v34, v34, v35
	v_cndmask_b32_e32 v64, v64, v63, vcc
	v_add_u32_e32 v63, 0xffffffa0, v62
	v_cndmask_b32_e64 v65, v100, v65, s[38:39]
	v_cvt_f32_i32_e32 v63, v63
	v_pk_mul_f32 v[64:65], v[64:65], s[64:65] op_sel_hi:[1,0]
	v_cmp_gt_i32_e32 vcc, s3, v62
	v_pk_mul_f32 v[36:37], v[64:65], v[36:37]
	v_add_u32_e32 v65, 0xffffff9f, v62
	v_cvt_f32_i32_e32 v65, v65
	v_mul_f32_e32 v64, v52, v63
	v_mul_f32_e32 v63, v57, v63
	v_exp_f32_e32 v64, v64
	v_exp_f32_e32 v63, v63
	v_mul_f32_e32 v100, v52, v65
	v_mul_f32_e32 v65, v57, v65
	v_exp_f32_e32 v100, v100
	v_exp_f32_e32 v65, v65
	v_cndmask_b32_e32 v64, v64, v63, vcc
	v_add_u32_e32 v63, 0xffffff9e, v62
	v_cvt_f32_i32_e32 v63, v63
	v_cmp_gt_i32_e64 s[38:39], s2, v62
	v_cmp_gt_i32_e32 vcc, s5, v62
	s_movk_i32 s2, 0x70
	v_cndmask_b32_e64 v65, v100, v65, s[38:39]
	v_pk_mul_f32 v[64:65], v[64:65], s[64:65] op_sel_hi:[1,0]
	v_cmp_gt_i32_e64 s[38:39], s6, v62
	v_pk_mul_f32 v[38:39], v[64:65], v[38:39]
	v_mul_f32_e32 v64, v52, v63
	v_mul_f32_e32 v63, v57, v63
	v_exp_f32_e32 v65, v63
	v_add_u32_e32 v63, 0xffffff9d, v62
	v_cvt_f32_i32_e32 v63, v63
	v_exp_f32_e32 v64, v64
	v_cvt_pk_bf16_f32 v35, v36, v37
	v_cvt_pk_bf16_f32 v36, v38, v39
	v_mul_f32_e32 v100, v52, v63
	v_mul_f32_e32 v63, v57, v63
	v_exp_f32_e32 v100, v100
	v_exp_f32_e32 v63, v63
	v_cndmask_b32_e32 v62, v64, v65, vcc
	v_cmp_gt_i32_e32 vcc, s2, v61
	s_movk_i32 s2, 0x71
	v_cndmask_b32_e64 v63, v100, v63, s[38:39]
	v_pk_mul_f32 v[62:63], v[62:63], s[64:65] op_sel_hi:[1,0]
	v_cmp_gt_i32_e64 s[38:39], s2, v61
	v_pk_mul_f32 v[40:41], v[62:63], v[40:41]
	v_add_u32_e32 v62, 0xffffff90, v61
	v_cvt_f32_i32_e32 v62, v62
	s_movk_i32 s2, 0x72
	v_cvt_pk_bf16_f32 v37, v40, v41
	v_readlane_b32 s6, v255, 27
	v_mul_f32_e32 v63, v52, v62
	v_exp_f32_e32 v64, v63
	v_add_u32_e32 v63, 0xffffff8f, v61
	v_cvt_f32_i32_e32 v63, v63
	v_mul_f32_e32 v62, v57, v62
	v_exp_f32_e32 v62, v62
	s_add_i32 s5, 0, 0x1c000
	v_mul_f32_e32 v65, v52, v63
	v_mul_f32_e32 v63, v57, v63
	v_exp_f32_e32 v65, v65
	v_exp_f32_e32 v63, v63
	v_cndmask_b32_e32 v62, v64, v62, vcc
	v_cmp_gt_i32_e32 vcc, s2, v61
	s_movk_i32 s2, 0x73
	v_cndmask_b32_e64 v63, v65, v63, s[38:39]
	v_pk_mul_f32 v[62:63], v[62:63], s[64:65] op_sel_hi:[1,0]
	v_cmp_gt_i32_e64 s[38:39], s2, v61
	v_pk_mul_f32 v[42:43], v[62:63], v[42:43]
	v_add_u32_e32 v62, 0xffffff8e, v61
	v_cvt_f32_i32_e32 v62, v62
	s_movk_i32 s2, 0x78
	v_cvt_pk_bf16_f32 v38, v42, v43
	s_add_i32 s3, 0, 0x16000
	v_mul_f32_e32 v63, v52, v62
	v_exp_f32_e32 v64, v63
	v_add_u32_e32 v63, 0xffffff8d, v61
	v_cvt_f32_i32_e32 v63, v63
	v_mul_f32_e32 v62, v57, v62
	v_exp_f32_e32 v62, v62
	v_mul_f32_e32 v65, v52, v63
	v_mul_f32_e32 v63, v57, v63
	v_exp_f32_e32 v65, v65
	v_exp_f32_e32 v63, v63
	v_cndmask_b32_e32 v62, v64, v62, vcc
	v_cmp_gt_i32_e32 vcc, s2, v61
	s_movk_i32 s2, 0x79
	v_cndmask_b32_e64 v63, v65, v63, s[38:39]
	v_pk_mul_f32 v[62:63], v[62:63], s[64:65] op_sel_hi:[1,0]
	v_cmp_gt_i32_e64 s[38:39], s2, v61
	v_pk_mul_f32 v[44:45], v[62:63], v[44:45]
	v_add_u32_e32 v62, 0xffffff88, v61
	v_cvt_f32_i32_e32 v62, v62
	s_movk_i32 s2, 0x7a
	v_cvt_pk_bf16_f32 v39, v44, v45
	v_mul_f32_e32 v63, v52, v62
	v_exp_f32_e32 v64, v63
	v_add_u32_e32 v63, 0xffffff87, v61
	v_cvt_f32_i32_e32 v63, v63
	v_mul_f32_e32 v62, v57, v62
	v_exp_f32_e32 v62, v62
	v_mul_f32_e32 v65, v52, v63
	v_mul_f32_e32 v63, v57, v63
	v_exp_f32_e32 v65, v65
	v_exp_f32_e32 v63, v63
	v_cndmask_b32_e32 v62, v64, v62, vcc
	v_cmp_gt_i32_e32 vcc, s2, v61
	s_movk_i32 s2, 0x7b
	v_cndmask_b32_e64 v63, v65, v63, s[38:39]
	v_pk_mul_f32 v[62:63], v[62:63], s[64:65] op_sel_hi:[1,0]
	v_cmp_gt_i32_e64 s[38:39], s2, v61
	v_pk_mul_f32 v[46:47], v[62:63], v[46:47]
	v_add_u32_e32 v62, 0xffffff86, v61
	v_cvt_f32_i32_e32 v62, v62
	v_cvt_pk_bf16_f32 v40, v46, v47
	s_add_i32 s2, 0, 0x1e000
	v_mul_f32_e32 v63, v52, v62
	v_exp_f32_e32 v64, v63
	v_add_u32_e32 v63, 0xffffff85, v61
	v_cvt_f32_i32_e32 v63, v63
	v_mul_f32_e32 v62, v57, v62
	v_exp_f32_e32 v62, v62
	v_mul_f32_e32 v65, v52, v63
	v_mul_f32_e32 v63, v57, v63
	v_exp_f32_e32 v65, v65
	v_exp_f32_e32 v63, v63
	v_cndmask_b32_e32 v62, v64, v62, vcc
	v_cmp_gt_u32_e32 vcc, 32, v110
	v_cndmask_b32_e64 v63, v65, v63, s[38:39]
	v_pk_mul_f32 v[62:63], v[62:63], s[64:65] op_sel_hi:[1,0]
	s_nop 0
	v_pk_mul_f32 v[48:49], v[62:63], v[48:49]
	s_nop 0
	v_cvt_pk_bf16_f32 v41, v48, v49
	ds_read_b64_tr_b16 v[42:43], v60 offset:57344
	ds_read_b64_tr_b16 v[44:45], v59 offset:57344
	ds_read_b64_tr_b16 v[46:47], v60 offset:61440
	ds_read_b64_tr_b16 v[48:49], v59 offset:61440
	s_waitcnt lgkmcnt(2)
	v_mfma_f32_32x32x16_bf16 v[18:33], v[42:45], v[34:37], v[18:33]
	s_waitcnt lgkmcnt(0)
	v_mfma_f32_32x32x16_bf16 v[18:33], v[46:49], v[38:41], v[18:33]
	ds_read_b64_tr_b16 v[42:43], v58 offset:57344
	ds_read_b64_tr_b16 v[44:45], v0 offset:57344
	ds_read_b64_tr_b16 v[46:47], v58 offset:61440
	ds_read_b64_tr_b16 v[48:49], v0 offset:61440
	v_add_u32_e32 v0, 1, v54
	v_cvt_f32_ubyte0_e32 v0, v0
	v_mul_f32_e32 v0, v52, v0
	v_exp_f32_e32 v0, v0
	s_waitcnt lgkmcnt(2)
	v_mfma_f32_32x32x16_bf16 v[2:17], v[42:45], v[34:37], v[2:17]
	v_sub_u32_e32 v34, 0x80, v54
	v_cvt_f32_ubyte0_e32 v34, v34
	v_mul_f32_e64 v34, -v57, v34
	v_exp_f32_e32 v108, v34
	v_or_b32_e32 v34, v50, v51
	v_lshlrev_b32_e32 v35, 1, v53
	v_lshl_or_b32 v115, v34, 8, v56
	v_or_b32_e32 v34, 4, v34
	v_and_b32_e32 v114, 2, v35
	v_bfe_u32 v116, v34, 2, 2
	v_lshl_or_b32 v117, v34, 8, v56
	v_bitop3_b32 v34, v112, v55, v114 bitop3:0x36
	v_bitop3_b32 v35, v116, v55, v112 bitop3:0x36
	v_lshl_add_u32 v118, v34, 4, v115
	v_lshl_add_u32 v119, v35, 4, v117
	s_waitcnt lgkmcnt(0)
	v_mfma_f32_32x32x16_bf16 v[2:17], v[46:49], v[38:41], v[2:17]
	v_add_u32_e32 v34, s9, v118
	v_add_u32_e32 v36, s9, v119
	v_add_u32_e32 v38, s14, v118
	v_add_u32_e32 v100, s6, v118
	ds_read_b64_tr_b16 v[34:35], v34
	ds_read_b64_tr_b16 v[36:37], v36
	ds_read_b64_tr_b16 v[50:51], v38
	ds_read_b64_tr_b16 v[100:101], v100
	v_add_u32_e32 v38, s14, v119
	ds_read_b64_tr_b16 v[52:53], v38
	v_add_u32_e32 v102, s6, v119
	v_add_u32_e32 v104, s18, v118
	v_add_u32_e32 v106, s18, v119
	ds_read_b64_tr_b16 v[102:103], v102
	ds_read_b64_tr_b16 v[104:105], v104
	ds_read_b64_tr_b16 v[106:107], v106
	s_waitcnt lgkmcnt(6)
	v_mfma_f32_32x32x16_bf16 v[34:49], v[34:37], v[94:97], 0
	s_waitcnt lgkmcnt(3)
	v_mfma_f32_32x32x16_bf16 v[50:65], v[50:53], v[94:97], 0
	s_waitcnt lgkmcnt(2)
	v_mfma_f32_32x32x16_bf16 v[34:49], v[100:103], v[90:93], v[34:49]
	v_add_u32_e32 v100, s16, v118
	v_add_u32_e32 v102, s16, v119
	ds_read_b64_tr_b16 v[100:101], v100
	ds_read_b64_tr_b16 v[102:103], v102
	s_waitcnt lgkmcnt(2)
	v_mfma_f32_32x32x16_bf16 v[50:65], v[104:107], v[90:93], v[50:65]
	v_add_u32_e32 v104, s17, v118
	v_add_u32_e32 v106, s17, v119
	ds_read_b64_tr_b16 v[104:105], v104
	ds_read_b64_tr_b16 v[106:107], v106
	s_waitcnt lgkmcnt(2)
	v_mfma_f32_32x32x16_bf16 v[34:49], v[100:103], v[86:89], v[34:49]
	v_add_u32_e32 v100, s10, v118
	v_add_u32_e32 v102, s10, v119
	ds_read_b64_tr_b16 v[100:101], v100
	ds_read_b64_tr_b16 v[102:103], v102
	s_waitcnt lgkmcnt(2)
	v_mfma_f32_32x32x16_bf16 v[50:65], v[104:107], v[86:89], v[50:65]
	v_add_u32_e32 v104, s19, v118
	v_add_u32_e32 v106, s19, v119
	ds_read_b64_tr_b16 v[104:105], v104
	ds_read_b64_tr_b16 v[106:107], v106
	s_waitcnt lgkmcnt(2)
	v_mfma_f32_32x32x16_bf16 v[34:49], v[100:103], v[82:85], v[34:49]
	v_add_u32_e32 v100, s7, v118
	v_add_u32_e32 v102, s7, v119
	ds_read_b64_tr_b16 v[100:101], v100
	ds_read_b64_tr_b16 v[102:103], v102
	s_waitcnt lgkmcnt(2)
	v_mfma_f32_32x32x16_bf16 v[50:65], v[104:107], v[82:85], v[50:65]
	v_add_u32_e32 v104, s5, v118
	v_add_u32_e32 v106, s5, v119
	ds_read_b64_tr_b16 v[104:105], v104
	ds_read_b64_tr_b16 v[106:107], v106
	s_waitcnt lgkmcnt(2)
	v_mfma_f32_32x32x16_bf16 v[34:49], v[100:103], v[78:81], v[34:49]
	v_add_u32_e32 v100, s11, v118
	v_add_u32_e32 v102, s11, v119
	ds_read_b64_tr_b16 v[100:101], v100
	ds_read_b64_tr_b16 v[102:103], v102
	s_waitcnt lgkmcnt(2)
	v_mfma_f32_32x32x16_bf16 v[50:65], v[104:107], v[78:81], v[50:65]
	v_add_u32_e32 v104, s20, v118
	v_add_u32_e32 v106, s20, v119
	ds_read_b64_tr_b16 v[104:105], v104
	ds_read_b64_tr_b16 v[106:107], v106
	s_waitcnt lgkmcnt(2)
	v_mfma_f32_32x32x16_bf16 v[34:49], v[100:103], v[74:77], v[34:49]
	v_add_u32_e32 v100, s3, v118
	v_add_u32_e32 v102, s3, v119
	ds_read_b64_tr_b16 v[100:101], v100
	ds_read_b64_tr_b16 v[102:103], v102
	s_waitcnt lgkmcnt(2)
	v_mfma_f32_32x32x16_bf16 v[50:65], v[104:107], v[74:77], v[50:65]
	v_add_u32_e32 v104, s2, v118
	v_add_u32_e32 v106, s2, v119
	ds_read_b64_tr_b16 v[104:105], v104
	ds_read_b64_tr_b16 v[106:107], v106
	s_waitcnt lgkmcnt(2)
	v_mfma_f32_32x32x16_bf16 v[34:49], v[100:103], v[70:73], v[34:49]
	v_add_u32_e32 v100, s12, v118
	v_add_u32_e32 v102, s12, v119
	ds_read_b64_tr_b16 v[100:101], v100
	ds_read_b64_tr_b16 v[102:103], v102
	s_waitcnt lgkmcnt(2)
	v_mfma_f32_32x32x16_bf16 v[50:65], v[104:107], v[70:73], v[50:65]
	v_add_u32_e32 v104, s21, v118
	v_add_u32_e32 v106, s21, v119
	ds_read_b64_tr_b16 v[104:105], v104
	ds_read_b64_tr_b16 v[106:107], v106
	s_waitcnt lgkmcnt(0)
	v_mfma_f32_32x32x16_bf16 v[50:65], v[104:107], v[66:69], v[50:65]
	v_mfma_f32_32x32x16_bf16 v[34:49], v[100:103], v[66:69], v[34:49]
	s_nop 10
	v_mul_f32_e64 v50, v108, v50
	v_mul_f32_e64 v51, v108, v51
	v_pk_fma_f32 v[34:35], v[0:1], v[34:35], v[50:51] op_sel_hi:[0,1,1]
	v_pk_add_f32 v[104:105], v[18:19], v[34:35]
	v_pk_mul_f32 v[18:19], v[108:109], v[52:53] op_sel_hi:[0,1]
	v_pk_fma_f32 v[18:19], v[0:1], v[36:37], v[18:19] op_sel_hi:[0,1,1]
	v_pk_add_f32 v[106:107], v[20:21], v[18:19]
	v_pk_mul_f32 v[18:19], v[108:109], v[54:55] op_sel_hi:[0,1]
	v_pk_fma_f32 v[18:19], v[0:1], v[38:39], v[18:19] op_sel_hi:[0,1,1]
	v_pk_add_f32 v[102:103], v[22:23], v[18:19]
	v_pk_mul_f32 v[18:19], v[108:109], v[56:57] op_sel_hi:[0,1]
	v_pk_fma_f32 v[18:19], v[0:1], v[40:41], v[18:19] op_sel_hi:[0,1,1]
	v_pk_add_f32 v[100:101], v[24:25], v[18:19]
	v_pk_mul_f32 v[18:19], v[108:109], v[58:59] op_sel_hi:[0,1]
	v_pk_fma_f32 v[18:19], v[0:1], v[42:43], v[18:19] op_sel_hi:[0,1,1]
	v_pk_add_f32 v[56:57], v[26:27], v[18:19]
	v_pk_mul_f32 v[18:19], v[108:109], v[60:61] op_sel_hi:[0,1]
	v_pk_fma_f32 v[18:19], v[0:1], v[44:45], v[18:19] op_sel_hi:[0,1,1]
	v_pk_add_f32 v[54:55], v[28:29], v[18:19]
	v_pk_mul_f32 v[18:19], v[108:109], v[62:63] op_sel_hi:[0,1]
	v_pk_fma_f32 v[18:19], v[0:1], v[46:47], v[18:19] op_sel_hi:[0,1,1]
	v_pk_add_f32 v[52:53], v[30:31], v[18:19]
	v_pk_mul_f32 v[18:19], v[108:109], v[64:65] op_sel_hi:[0,1]
	v_pk_fma_f32 v[18:19], v[0:1], v[48:49], v[18:19] op_sel_hi:[0,1,1]
	v_pk_add_f32 v[50:51], v[32:33], v[18:19]
	v_bitop3_b32 v18, v112, v113, v114 bitop3:0x36
	v_bitop3_b32 v19, v116, v113, v112 bitop3:0x36
	v_lshl_add_u32 v112, v18, 4, v115
	v_lshl_add_u32 v113, v19, 4, v117
	v_add_u32_e32 v18, s9, v112
	v_add_u32_e32 v20, s9, v113
	v_add_u32_e32 v22, s14, v112
	v_add_u32_e32 v58, s6, v112
	ds_read_b64_tr_b16 v[18:19], v18
	ds_read_b64_tr_b16 v[20:21], v20
	ds_read_b64_tr_b16 v[34:35], v22
	ds_read_b64_tr_b16 v[58:59], v58
	v_add_u32_e32 v22, s14, v113
	ds_read_b64_tr_b16 v[36:37], v22
	v_add_u32_e32 v60, s6, v113
	v_add_u32_e32 v62, s18, v112
	v_add_u32_e32 v64, s18, v113
	ds_read_b64_tr_b16 v[60:61], v60
	ds_read_b64_tr_b16 v[62:63], v62
	ds_read_b64_tr_b16 v[64:65], v64
	s_waitcnt lgkmcnt(6)
	v_mfma_f32_32x32x16_bf16 v[18:33], v[18:21], v[94:97], 0
	s_waitcnt lgkmcnt(3)
	v_mfma_f32_32x32x16_bf16 v[34:49], v[34:37], v[94:97], 0
	s_waitcnt lgkmcnt(2)
	v_mfma_f32_32x32x16_bf16 v[18:33], v[58:61], v[90:93], v[18:33]
	v_add_u32_e32 v58, s16, v112
	v_add_u32_e32 v60, s16, v113
	ds_read_b64_tr_b16 v[58:59], v58
	ds_read_b64_tr_b16 v[60:61], v60
	s_waitcnt lgkmcnt(2)
	v_mfma_f32_32x32x16_bf16 v[34:49], v[62:65], v[90:93], v[34:49]
	v_add_u32_e32 v62, s17, v112
	v_add_u32_e32 v64, s17, v113
	ds_read_b64_tr_b16 v[62:63], v62
	ds_read_b64_tr_b16 v[64:65], v64
	s_waitcnt lgkmcnt(2)
	v_mfma_f32_32x32x16_bf16 v[18:33], v[58:61], v[86:89], v[18:33]
	v_add_u32_e32 v58, s10, v112
	v_add_u32_e32 v60, s10, v113
	ds_read_b64_tr_b16 v[58:59], v58
	ds_read_b64_tr_b16 v[60:61], v60
	s_waitcnt lgkmcnt(2)
	v_mfma_f32_32x32x16_bf16 v[34:49], v[62:65], v[86:89], v[34:49]
	v_add_u32_e32 v62, s19, v112
	v_add_u32_e32 v64, s19, v113
	ds_read_b64_tr_b16 v[62:63], v62
	ds_read_b64_tr_b16 v[64:65], v64
	s_waitcnt lgkmcnt(2)
	v_mfma_f32_32x32x16_bf16 v[18:33], v[58:61], v[82:85], v[18:33]
	v_add_u32_e32 v58, s7, v112
	v_add_u32_e32 v60, s7, v113
	ds_read_b64_tr_b16 v[58:59], v58
	ds_read_b64_tr_b16 v[60:61], v60
	s_waitcnt lgkmcnt(2)
	v_mfma_f32_32x32x16_bf16 v[34:49], v[62:65], v[82:85], v[34:49]
	v_add_u32_e32 v62, s5, v112
	v_add_u32_e32 v64, s5, v113
	ds_read_b64_tr_b16 v[62:63], v62
	ds_read_b64_tr_b16 v[64:65], v64
	s_waitcnt lgkmcnt(2)
	v_mfma_f32_32x32x16_bf16 v[18:33], v[58:61], v[78:81], v[18:33]
	v_add_u32_e32 v58, s11, v112
	v_add_u32_e32 v60, s11, v113
	ds_read_b64_tr_b16 v[58:59], v58
	ds_read_b64_tr_b16 v[60:61], v60
	s_waitcnt lgkmcnt(2)
	v_mfma_f32_32x32x16_bf16 v[34:49], v[62:65], v[78:81], v[34:49]
	v_add_u32_e32 v62, s20, v112
	v_add_u32_e32 v64, s20, v113
	ds_read_b64_tr_b16 v[62:63], v62
	ds_read_b64_tr_b16 v[64:65], v64
	s_waitcnt lgkmcnt(2)
	v_mfma_f32_32x32x16_bf16 v[18:33], v[58:61], v[74:77], v[18:33]
	v_add_u32_e32 v58, s3, v112
	v_add_u32_e32 v60, s3, v113
	ds_read_b64_tr_b16 v[58:59], v58
	ds_read_b64_tr_b16 v[60:61], v60
	s_waitcnt lgkmcnt(2)
	v_mfma_f32_32x32x16_bf16 v[34:49], v[62:65], v[74:77], v[34:49]
	v_add_u32_e32 v62, s2, v112
	v_add_u32_e32 v64, s2, v113
	ds_read_b64_tr_b16 v[62:63], v62
	ds_read_b64_tr_b16 v[64:65], v64
	s_lshl_b32 s2, s8, 7
	s_waitcnt lgkmcnt(2)
	v_mfma_f32_32x32x16_bf16 v[18:33], v[58:61], v[70:73], v[18:33]
	v_add_u32_e32 v58, s12, v112
	v_add_u32_e32 v60, s12, v113
	ds_read_b64_tr_b16 v[58:59], v58
	ds_read_b64_tr_b16 v[60:61], v60
	s_waitcnt lgkmcnt(2)
	v_mfma_f32_32x32x16_bf16 v[34:49], v[62:65], v[70:73], v[34:49]
	v_add_u32_e32 v62, s21, v112
	v_add_u32_e32 v64, s21, v113
	ds_read_b64_tr_b16 v[62:63], v62
	ds_read_b64_tr_b16 v[64:65], v64
	s_waitcnt lgkmcnt(0)
	v_mfma_f32_32x32x16_bf16 v[34:49], v[62:65], v[66:69], v[34:49]
	v_mfma_f32_32x32x16_bf16 v[18:33], v[58:61], v[66:69], v[18:33]
	s_nop 10
	v_mul_f32_e64 v34, v108, v34
	v_mul_f32_e64 v35, v108, v35
	v_pk_fma_f32 v[18:19], v[0:1], v[18:19], v[34:35] op_sel_hi:[0,1,1]
	v_pk_add_f32 v[58:59], v[2:3], v[18:19]
	v_pk_mul_f32 v[2:3], v[108:109], v[36:37] op_sel_hi:[0,1]
	v_pk_fma_f32 v[2:3], v[0:1], v[20:21], v[2:3] op_sel_hi:[0,1,1]
	v_pk_add_f32 v[34:35], v[4:5], v[2:3]
	v_pk_mul_f32 v[2:3], v[108:109], v[38:39] op_sel_hi:[0,1]
	v_pk_fma_f32 v[2:3], v[0:1], v[22:23], v[2:3] op_sel_hi:[0,1,1]
	v_pk_add_f32 v[20:21], v[6:7], v[2:3]
	v_pk_mul_f32 v[2:3], v[108:109], v[40:41] op_sel_hi:[0,1]
	v_pk_fma_f32 v[2:3], v[0:1], v[24:25], v[2:3] op_sel_hi:[0,1,1]
	v_pk_add_f32 v[18:19], v[8:9], v[2:3]
	v_pk_mul_f32 v[2:3], v[108:109], v[42:43] op_sel_hi:[0,1]
	v_pk_fma_f32 v[2:3], v[0:1], v[26:27], v[2:3] op_sel_hi:[0,1,1]
	v_pk_add_f32 v[8:9], v[10:11], v[2:3]
	v_pk_mul_f32 v[2:3], v[108:109], v[44:45] op_sel_hi:[0,1]
	v_pk_fma_f32 v[2:3], v[0:1], v[28:29], v[2:3] op_sel_hi:[0,1,1]
	v_pk_add_f32 v[6:7], v[12:13], v[2:3]
	v_pk_mul_f32 v[2:3], v[108:109], v[46:47] op_sel_hi:[0,1]
	v_pk_fma_f32 v[2:3], v[0:1], v[30:31], v[2:3] op_sel_hi:[0,1,1]
	v_pk_add_f32 v[4:5], v[14:15], v[2:3]
	v_pk_mul_f32 v[2:3], v[108:109], v[48:49] op_sel_hi:[0,1]
	v_pk_fma_f32 v[2:3], v[0:1], v[32:33], v[2:3] op_sel_hi:[0,1,1]
	v_mul_f32_e32 v0, v105, v105
	v_pk_fma_f32 v[10:11], v[104:105], v[104:105], v[0:1] op_sel_hi:[1,1,0]
	v_mul_f32_e32 v0, v107, v107
	v_pk_fma_f32 v[10:11], v[106:107], v[106:107], v[10:11]
	v_pk_add_f32 v[2:3], v[16:17], v[2:3]
	v_pk_add_f32 v[10:11], v[0:1], v[10:11] op_sel_hi:[0,1]
	v_pk_fma_f32 v[10:11], v[102:103], v[102:103], v[10:11]
	v_mul_f32_e32 v0, v103, v103
	v_pk_add_f32 v[10:11], v[0:1], v[10:11] op_sel_hi:[0,1]
	v_pk_fma_f32 v[10:11], v[100:101], v[100:101], v[10:11]
	v_mul_f32_e32 v0, v101, v101
	v_pk_add_f32 v[10:11], v[0:1], v[10:11] op_sel_hi:[0,1]
	v_pk_fma_f32 v[10:11], v[56:57], v[56:57], v[10:11]
	v_mul_f32_e32 v0, v57, v57
	v_pk_add_f32 v[10:11], v[0:1], v[10:11] op_sel_hi:[0,1]
	v_pk_fma_f32 v[10:11], v[54:55], v[54:55], v[10:11]
	v_mul_f32_e32 v0, v55, v55
	v_pk_add_f32 v[10:11], v[0:1], v[10:11] op_sel_hi:[0,1]
	v_pk_fma_f32 v[10:11], v[52:53], v[52:53], v[10:11]
	v_mul_f32_e32 v0, v53, v53
	v_pk_add_f32 v[10:11], v[0:1], v[10:11] op_sel_hi:[0,1]
	v_pk_fma_f32 v[10:11], v[50:51], v[50:51], v[10:11]
	v_mul_f32_e32 v0, v51, v51
	v_pk_add_f32 v[10:11], v[0:1], v[10:11] op_sel_hi:[0,1]
	v_pk_fma_f32 v[10:11], v[58:59], v[58:59], v[10:11]
	v_mul_f32_e32 v0, v59, v59
	v_pk_add_f32 v[10:11], v[0:1], v[10:11] op_sel_hi:[0,1]
	v_pk_fma_f32 v[10:11], v[34:35], v[34:35], v[10:11]
	v_mul_f32_e32 v0, v35, v35
	v_pk_add_f32 v[10:11], v[0:1], v[10:11] op_sel_hi:[0,1]
	v_pk_fma_f32 v[10:11], v[20:21], v[20:21], v[10:11]
	v_mul_f32_e32 v0, v21, v21
	v_pk_add_f32 v[10:11], v[0:1], v[10:11] op_sel_hi:[0,1]
	v_pk_fma_f32 v[10:11], v[18:19], v[18:19], v[10:11]
	v_mul_f32_e32 v0, v19, v19
	v_pk_add_f32 v[10:11], v[0:1], v[10:11] op_sel_hi:[0,1]
	v_pk_fma_f32 v[10:11], v[8:9], v[8:9], v[10:11]
	v_mul_f32_e32 v0, v9, v9
	v_pk_add_f32 v[10:11], v[0:1], v[10:11] op_sel_hi:[0,1]
	v_pk_fma_f32 v[10:11], v[6:7], v[6:7], v[10:11]
	v_mul_f32_e32 v0, v7, v7
	v_pk_add_f32 v[10:11], v[0:1], v[10:11] op_sel_hi:[0,1]
	v_pk_fma_f32 v[10:11], v[4:5], v[4:5], v[10:11]
	v_mul_f32_e32 v0, v5, v5
	v_pk_add_f32 v[10:11], v[0:1], v[10:11] op_sel_hi:[0,1]
	v_pk_fma_f32 v[10:11], v[2:3], v[2:3], v[10:11]
	v_mul_f32_e32 v0, v3, v3
	v_pk_add_f32 v[10:11], v[0:1], v[10:11] op_sel_hi:[0,1]
	v_mov_b32_e32 v0, v10
	s_nop 1
	v_permlane32_swap_b32_e32 v10, v0
	s_and_saveexec_b64 s[8:9], vcc
	s_cbranch_execz .LBB0_475
	s_add_i32 s3, s2, 0
	v_add_f32_e32 v0, v10, v0
	v_lshl_add_u32 v10, v110, 2, s3
	v_add_u32_e32 v10, 0x20000, v10
	ds_write_b32 v10, v0
	s_branch .LBB0_475
